# v6 minus all s_setprio in the 8 GEMM K-loops
# speedup vs baseline: 1.0251x; 1.0066x over previous
.LBB0_109:
	ds_read_b128 v[130:133], v158
	ds_read_b128 v[162:165], v158 offset:1024
	ds_read_b128 v[166:169], v158 offset:2048
	ds_read_b128 v[170:173], v158 offset:3072
	ds_read_b128 v[174:177], v159
	ds_read_b128 v[178:181], v159 offset:1024
	ds_read_b128 v[182:185], v159 offset:2048
	ds_read_b128 v[186:189], v159 offset:3072
	s_add_u32 s22, s20, 0xfff04000
	s_addc_u32 s23, s21, -1
	s_cmp_eq_u32 s46, 60
	s_cselect_b32 s26, s42, s22
	s_cselect_b32 s27, s15, s23
	s_cselect_b32 s24, s43, s44
	s_cselect_b32 s25, s13, s45
	s_add_u32 s22, s26, 0x4000
	s_addc_u32 s23, s27, 0
	s_add_i32 m0, s29, 0xc000
	ds_read_b128 v[190:193], v160
	ds_read_b128 v[194:197], v160 offset:1024
	ds_read_b128 v[198:201], v160 offset:2048
	ds_read_b128 v[202:205], v160 offset:3072
	ds_read_b128 v[206:209], v160 offset:4096
	ds_read_b128 v[210:213], v160 offset:5120
	ds_read_b128 v[214:217], v160 offset:6144
	ds_read_b128 v[218:221], v160 offset:7168
	global_load_lds_dwordx4 v146, s[20:21]
	s_add_i32 m0, s29, 0xe000
	s_nop 0
	global_load_lds_dwordx4 v148, s[20:21]
	s_waitcnt vmcnt(8)
	s_waitcnt lgkmcnt(0)
	s_barrier
	s_waitcnt lgkmcnt(0)
	v_mfma_f32_16x16x32_bf16 v[62:65], v[130:133], v[190:193], v[62:65]
	v_mfma_f32_16x16x32_bf16 v[62:65], v[162:165], v[194:197], v[62:65]
	v_mfma_f32_16x16x32_bf16 v[58:61], v[166:169], v[190:193], v[58:61]
	v_mfma_f32_16x16x32_bf16 v[58:61], v[170:173], v[194:197], v[58:61]
	v_mfma_f32_16x16x32_bf16 v[54:57], v[130:133], v[198:201], v[54:57]
	v_mfma_f32_16x16x32_bf16 v[54:57], v[162:165], v[202:205], v[54:57]
	v_mfma_f32_16x16x32_bf16 v[50:53], v[166:169], v[198:201], v[50:53]
	v_mfma_f32_16x16x32_bf16 v[50:53], v[170:173], v[202:205], v[50:53]
	v_mfma_f32_16x16x32_bf16 v[46:49], v[130:133], v[206:209], v[46:49]
	v_mfma_f32_16x16x32_bf16 v[46:49], v[162:165], v[210:213], v[46:49]
	v_mfma_f32_16x16x32_bf16 v[42:45], v[166:169], v[206:209], v[42:45]
	v_mfma_f32_16x16x32_bf16 v[42:45], v[170:173], v[210:213], v[42:45]
	v_mfma_f32_16x16x32_bf16 v[38:41], v[130:133], v[214:217], v[38:41]
	v_mfma_f32_16x16x32_bf16 v[38:41], v[162:165], v[218:221], v[38:41]
	v_mfma_f32_16x16x32_bf16 v[34:37], v[166:169], v[214:217], v[34:37]
	v_mfma_f32_16x16x32_bf16 v[34:37], v[170:173], v[218:221], v[34:37]
	v_mfma_f32_16x16x32_bf16 v[126:129], v[174:177], v[190:193], v[126:129]
	v_mfma_f32_16x16x32_bf16 v[126:129], v[178:181], v[194:197], v[126:129]
	v_mfma_f32_16x16x32_bf16 v[122:125], v[182:185], v[190:193], v[122:125]
	v_mfma_f32_16x16x32_bf16 v[122:125], v[186:189], v[194:197], v[122:125]
	v_mfma_f32_16x16x32_bf16 v[118:121], v[174:177], v[198:201], v[118:121]
	v_mfma_f32_16x16x32_bf16 v[118:121], v[178:181], v[202:205], v[118:121]
	v_mfma_f32_16x16x32_bf16 v[114:117], v[182:185], v[198:201], v[114:117]
	v_mfma_f32_16x16x32_bf16 v[114:117], v[186:189], v[202:205], v[114:117]
	v_mfma_f32_16x16x32_bf16 v[110:113], v[174:177], v[206:209], v[110:113]
	v_mfma_f32_16x16x32_bf16 v[110:113], v[178:181], v[210:213], v[110:113]
	v_mfma_f32_16x16x32_bf16 v[106:109], v[182:185], v[206:209], v[106:109]
	v_mfma_f32_16x16x32_bf16 v[106:109], v[186:189], v[210:213], v[106:109]
	v_mfma_f32_16x16x32_bf16 v[102:105], v[174:177], v[214:217], v[102:105]
	v_mfma_f32_16x16x32_bf16 v[102:105], v[178:181], v[218:221], v[102:105]
	v_mfma_f32_16x16x32_bf16 v[98:101], v[182:185], v[214:217], v[98:101]
	v_mfma_f32_16x16x32_bf16 v[98:101], v[186:189], v[218:221], v[98:101]
	s_barrier
	s_add_i32 s47, s36, s28
	s_mov_b32 m0, s47
	ds_read_b128 v[190:193], v160 offset:16384
	ds_read_b128 v[194:197], v160 offset:17408
	ds_read_b128 v[198:201], v160 offset:18432
	ds_read_b128 v[202:205], v160 offset:19456
	ds_read_b128 v[206:209], v160 offset:20480
	ds_read_b128 v[210:213], v160 offset:21504
	ds_read_b128 v[214:217], v160 offset:22528
	ds_read_b128 v[218:221], v160 offset:23552
	global_load_lds_dwordx4 v138, s[24:25]
	s_add_i32 m0, s47, 0x2000
	s_add_u32 s48, s24, 0x100000
	s_addc_u32 s49, s25, 0
	s_add_i32 s47, s37, s28
	global_load_lds_dwordx4 v134, s[24:25]
	s_mov_b32 m0, s47
	s_nop 0
	global_load_lds_dwordx4 v138, s[48:49]
	s_add_i32 m0, s47, 0x2000
	s_nop 0
	global_load_lds_dwordx4 v134, s[48:49]
	s_mov_b32 m0, s29
	s_nop 0
	global_load_lds_dwordx4 v140, s[26:27]
	s_mov_b32 m0, s30
	s_nop 0
	global_load_lds_dwordx4 v136, s[26:27]
	s_waitcnt vmcnt(8)
	s_waitcnt lgkmcnt(0)
	s_barrier
	s_waitcnt lgkmcnt(0)
	v_mfma_f32_16x16x32_bf16 v[30:33], v[130:133], v[190:193], v[30:33]
	v_mfma_f32_16x16x32_bf16 v[30:33], v[162:165], v[194:197], v[30:33]
	v_mfma_f32_16x16x32_bf16 v[26:29], v[166:169], v[190:193], v[26:29]
	v_mfma_f32_16x16x32_bf16 v[26:29], v[170:173], v[194:197], v[26:29]
	v_mfma_f32_16x16x32_bf16 v[22:25], v[130:133], v[198:201], v[22:25]
	v_mfma_f32_16x16x32_bf16 v[22:25], v[162:165], v[202:205], v[22:25]
	v_mfma_f32_16x16x32_bf16 v[18:21], v[166:169], v[198:201], v[18:21]
	v_mfma_f32_16x16x32_bf16 v[18:21], v[170:173], v[202:205], v[18:21]
	v_mfma_f32_16x16x32_bf16 v[14:17], v[130:133], v[206:209], v[14:17]
	v_mfma_f32_16x16x32_bf16 v[14:17], v[162:165], v[210:213], v[14:17]
	v_mfma_f32_16x16x32_bf16 v[10:13], v[166:169], v[206:209], v[10:13]
	v_mfma_f32_16x16x32_bf16 v[10:13], v[170:173], v[210:213], v[10:13]
	v_mfma_f32_16x16x32_bf16 v[6:9], v[130:133], v[214:217], v[6:9]
	v_mfma_f32_16x16x32_bf16 v[6:9], v[162:165], v[218:221], v[6:9]
	v_mfma_f32_16x16x32_bf16 v[2:5], v[166:169], v[214:217], v[2:5]
	v_mfma_f32_16x16x32_bf16 v[2:5], v[170:173], v[218:221], v[2:5]
	v_mfma_f32_16x16x32_bf16 v[94:97], v[174:177], v[190:193], v[94:97]
	v_mfma_f32_16x16x32_bf16 v[94:97], v[178:181], v[194:197], v[94:97]
	v_mfma_f32_16x16x32_bf16 v[90:93], v[182:185], v[190:193], v[90:93]
	v_mfma_f32_16x16x32_bf16 v[90:93], v[186:189], v[194:197], v[90:93]
	v_mfma_f32_16x16x32_bf16 v[86:89], v[174:177], v[198:201], v[86:89]
	v_mfma_f32_16x16x32_bf16 v[86:89], v[178:181], v[202:205], v[86:89]
	v_mfma_f32_16x16x32_bf16 v[82:85], v[182:185], v[198:201], v[82:85]
	v_mfma_f32_16x16x32_bf16 v[82:85], v[186:189], v[202:205], v[82:85]
	v_mfma_f32_16x16x32_bf16 v[78:81], v[174:177], v[206:209], v[78:81]
	v_mfma_f32_16x16x32_bf16 v[78:81], v[178:181], v[210:213], v[78:81]
	v_mfma_f32_16x16x32_bf16 v[74:77], v[182:185], v[206:209], v[74:77]
	v_mfma_f32_16x16x32_bf16 v[74:77], v[186:189], v[210:213], v[74:77]
	v_mfma_f32_16x16x32_bf16 v[70:73], v[174:177], v[214:217], v[70:73]
	v_mfma_f32_16x16x32_bf16 v[70:73], v[178:181], v[218:221], v[70:73]
	v_mfma_f32_16x16x32_bf16 v[66:69], v[182:185], v[214:217], v[66:69]
	v_mfma_f32_16x16x32_bf16 v[66:69], v[186:189], v[218:221], v[66:69]
	s_barrier
	s_add_i32 s47, 0, 0x18000
	v_add_u32_e32 v154, s47, v156
	s_add_i32 s48, 0, 0x1c000
	ds_read_b128 v[130:133], v154
	ds_read_b128 v[162:165], v154 offset:1024
	ds_read_b128 v[166:169], v154 offset:2048
	ds_read_b128 v[170:173], v154 offset:3072
	v_add_u32_e32 v154, s48, v156
	ds_read_b128 v[174:177], v154
	ds_read_b128 v[178:181], v154 offset:1024
	ds_read_b128 v[182:185], v154 offset:2048
	ds_read_b128 v[186:189], v154 offset:3072
	s_add_u32 s26, s26, 0x100000
	s_addc_u32 s27, s27, 0
	s_mov_b32 m0, s31
	ds_read_b128 v[190:193], v160 offset:32768
	ds_read_b128 v[194:197], v160 offset:33792
	ds_read_b128 v[198:201], v160 offset:34816
	ds_read_b128 v[202:205], v160 offset:35840
	ds_read_b128 v[206:209], v160 offset:36864
	ds_read_b128 v[210:213], v160 offset:37888
	ds_read_b128 v[214:217], v160 offset:38912
	ds_read_b128 v[218:221], v160 offset:39936
	global_load_lds_dwordx4 v140, s[26:27]
	s_mov_b32 m0, s33
	s_nop 0
	global_load_lds_dwordx4 v136, s[26:27]
	s_waitcnt vmcnt(8)
	s_waitcnt lgkmcnt(0)
	s_barrier
	s_waitcnt lgkmcnt(0)
	v_mfma_f32_16x16x32_bf16 v[62:65], v[130:133], v[190:193], v[62:65]
	v_mfma_f32_16x16x32_bf16 v[62:65], v[162:165], v[194:197], v[62:65]
	v_mfma_f32_16x16x32_bf16 v[58:61], v[166:169], v[190:193], v[58:61]
	v_mfma_f32_16x16x32_bf16 v[58:61], v[170:173], v[194:197], v[58:61]
	v_mfma_f32_16x16x32_bf16 v[54:57], v[130:133], v[198:201], v[54:57]
	v_mfma_f32_16x16x32_bf16 v[54:57], v[162:165], v[202:205], v[54:57]
	v_mfma_f32_16x16x32_bf16 v[50:53], v[166:169], v[198:201], v[50:53]
	v_mfma_f32_16x16x32_bf16 v[50:53], v[170:173], v[202:205], v[50:53]
	v_mfma_f32_16x16x32_bf16 v[46:49], v[130:133], v[206:209], v[46:49]
	v_mfma_f32_16x16x32_bf16 v[46:49], v[162:165], v[210:213], v[46:49]
	v_mfma_f32_16x16x32_bf16 v[42:45], v[166:169], v[206:209], v[42:45]
	v_mfma_f32_16x16x32_bf16 v[42:45], v[170:173], v[210:213], v[42:45]
	v_mfma_f32_16x16x32_bf16 v[38:41], v[130:133], v[214:217], v[38:41]
	v_mfma_f32_16x16x32_bf16 v[38:41], v[162:165], v[218:221], v[38:41]
	v_mfma_f32_16x16x32_bf16 v[34:37], v[166:169], v[214:217], v[34:37]
	v_mfma_f32_16x16x32_bf16 v[34:37], v[170:173], v[218:221], v[34:37]
	v_mfma_f32_16x16x32_bf16 v[126:129], v[174:177], v[190:193], v[126:129]
	v_mfma_f32_16x16x32_bf16 v[126:129], v[178:181], v[194:197], v[126:129]
	v_mfma_f32_16x16x32_bf16 v[122:125], v[182:185], v[190:193], v[122:125]
	v_mfma_f32_16x16x32_bf16 v[122:125], v[186:189], v[194:197], v[122:125]
	v_mfma_f32_16x16x32_bf16 v[118:121], v[174:177], v[198:201], v[118:121]
	v_mfma_f32_16x16x32_bf16 v[118:121], v[178:181], v[202:205], v[118:121]
	v_mfma_f32_16x16x32_bf16 v[114:117], v[182:185], v[198:201], v[114:117]
	v_mfma_f32_16x16x32_bf16 v[114:117], v[186:189], v[202:205], v[114:117]
	v_mfma_f32_16x16x32_bf16 v[110:113], v[174:177], v[206:209], v[110:113]
	v_mfma_f32_16x16x32_bf16 v[110:113], v[178:181], v[210:213], v[110:113]
	v_mfma_f32_16x16x32_bf16 v[106:109], v[182:185], v[206:209], v[106:109]
	v_mfma_f32_16x16x32_bf16 v[106:109], v[186:189], v[210:213], v[106:109]
	v_mfma_f32_16x16x32_bf16 v[102:105], v[174:177], v[214:217], v[102:105]
	v_mfma_f32_16x16x32_bf16 v[102:105], v[178:181], v[218:221], v[102:105]
	v_mfma_f32_16x16x32_bf16 v[98:101], v[182:185], v[214:217], v[98:101]
	v_mfma_f32_16x16x32_bf16 v[98:101], v[186:189], v[218:221], v[98:101]
	s_barrier
	s_add_u32 s26, s24, 0x4000
	s_addc_u32 s27, s25, 0
	s_add_i32 s47, s47, s28
	s_mov_b32 m0, s47
	ds_read_b128 v[190:193], v160 offset:49152
	ds_read_b128 v[194:197], v160 offset:50176
	ds_read_b128 v[198:201], v160 offset:51200
	ds_read_b128 v[202:205], v160 offset:52224
	ds_read_b128 v[206:209], v160 offset:53248
	ds_read_b128 v[210:213], v160 offset:54272
	ds_read_b128 v[214:217], v160 offset:55296
	ds_read_b128 v[218:221], v160 offset:56320
	global_load_lds_dwordx4 v138, s[26:27]
	s_add_i32 m0, s47, 0x2000
	s_add_u32 s24, s24, 0x104000
	s_addc_u32 s25, s25, 0
	global_load_lds_dwordx4 v134, s[26:27]
	s_add_i32 s26, s48, s28
	s_mov_b32 m0, s26
	s_nop 0
	global_load_lds_dwordx4 v138, s[24:25]
	s_add_i32 m0, s26, 0x2000
	s_nop 0
	global_load_lds_dwordx4 v134, s[24:25]
	s_mov_b32 m0, s34
	s_nop 0
	global_load_lds_dwordx4 v140, s[22:23]
	s_mov_b32 m0, s35
	s_nop 0
	global_load_lds_dwordx4 v136, s[22:23]
	s_waitcnt vmcnt(8)
	s_waitcnt lgkmcnt(0)
	s_barrier
	s_waitcnt lgkmcnt(0)
	v_mfma_f32_16x16x32_bf16 v[30:33], v[130:133], v[190:193], v[30:33]
	v_mfma_f32_16x16x32_bf16 v[30:33], v[162:165], v[194:197], v[30:33]
	v_mfma_f32_16x16x32_bf16 v[26:29], v[166:169], v[190:193], v[26:29]
	v_mfma_f32_16x16x32_bf16 v[26:29], v[170:173], v[194:197], v[26:29]
	v_mfma_f32_16x16x32_bf16 v[22:25], v[130:133], v[198:201], v[22:25]
	v_mfma_f32_16x16x32_bf16 v[22:25], v[162:165], v[202:205], v[22:25]
	v_mfma_f32_16x16x32_bf16 v[18:21], v[166:169], v[198:201], v[18:21]
	v_mfma_f32_16x16x32_bf16 v[18:21], v[170:173], v[202:205], v[18:21]
	v_mfma_f32_16x16x32_bf16 v[14:17], v[130:133], v[206:209], v[14:17]
	v_mfma_f32_16x16x32_bf16 v[14:17], v[162:165], v[210:213], v[14:17]
	v_mfma_f32_16x16x32_bf16 v[10:13], v[166:169], v[206:209], v[10:13]
	v_mfma_f32_16x16x32_bf16 v[10:13], v[170:173], v[210:213], v[10:13]
	v_mfma_f32_16x16x32_bf16 v[6:9], v[130:133], v[214:217], v[6:9]
	v_mfma_f32_16x16x32_bf16 v[6:9], v[162:165], v[218:221], v[6:9]
	v_mfma_f32_16x16x32_bf16 v[2:5], v[166:169], v[214:217], v[2:5]
	v_mfma_f32_16x16x32_bf16 v[2:5], v[170:173], v[218:221], v[2:5]
	v_mfma_f32_16x16x32_bf16 v[94:97], v[174:177], v[190:193], v[94:97]
	v_mfma_f32_16x16x32_bf16 v[94:97], v[178:181], v[194:197], v[94:97]
	v_mfma_f32_16x16x32_bf16 v[90:93], v[182:185], v[190:193], v[90:93]
	v_mfma_f32_16x16x32_bf16 v[90:93], v[186:189], v[194:197], v[90:93]
	v_mfma_f32_16x16x32_bf16 v[86:89], v[174:177], v[198:201], v[86:89]
	v_mfma_f32_16x16x32_bf16 v[86:89], v[178:181], v[202:205], v[86:89]
	v_mfma_f32_16x16x32_bf16 v[82:85], v[182:185], v[198:201], v[82:85]
	v_mfma_f32_16x16x32_bf16 v[82:85], v[186:189], v[202:205], v[82:85]
	v_mfma_f32_16x16x32_bf16 v[78:81], v[174:177], v[206:209], v[78:81]
	v_mfma_f32_16x16x32_bf16 v[78:81], v[178:181], v[210:213], v[78:81]
	v_mfma_f32_16x16x32_bf16 v[74:77], v[182:185], v[206:209], v[74:77]
	v_mfma_f32_16x16x32_bf16 v[74:77], v[186:189], v[210:213], v[74:77]
	v_mfma_f32_16x16x32_bf16 v[70:73], v[174:177], v[214:217], v[70:73]
	v_mfma_f32_16x16x32_bf16 v[70:73], v[178:181], v[218:221], v[70:73]
	v_mfma_f32_16x16x32_bf16 v[66:69], v[182:185], v[214:217], v[66:69]
	v_mfma_f32_16x16x32_bf16 v[66:69], v[186:189], v[218:221], v[66:69]
	s_barrier
	s_add_i32 s46, s46, 2
	s_add_u32 s20, s20, 0x8000
	s_addc_u32 s21, s21, 0
	s_add_u32 s44, s44, 0x8000
	s_addc_u32 s45, s45, 0
	s_cmp_gt_u32 s46, 61
	s_cbranch_scc0 .LBB0_109
	s_and_b64 vcc, exec, s[8:9]
	s_cbranch_vccnz .LBB0_113
	v_lshl_add_u32 v154, s4, 8, v1
	s_cmp_lg_u32 s41, 24
	s_mov_b64 s[20:21], -1
	s_cbranch_scc1 .LBB0_114

.LBB0_376:
	ds_read_b128 v[130:133], v159
	ds_read_b128 v[162:165], v159 offset:1024
	ds_read_b128 v[166:169], v159 offset:2048
	ds_read_b128 v[170:173], v159 offset:3072
	ds_read_b128 v[174:177], v160
	ds_read_b128 v[178:181], v160 offset:1024
	ds_read_b128 v[182:185], v160 offset:2048
	ds_read_b128 v[186:189], v160 offset:3072
	s_add_u32 s34, s26, 0xfff04000
	s_addc_u32 s35, s27, -1
	s_cmp_eq_u32 s87, 60
	s_cselect_b32 s38, s80, s34
	s_cselect_b32 s39, s21, s35
	s_cselect_b32 s36, s81, s83
	s_cselect_b32 s37, s19, s86
	s_add_u32 s34, s38, 0x4000
	s_addc_u32 s35, s39, 0
	s_add_i32 m0, s46, 0xc000
	ds_read_b128 v[190:193], v161
	ds_read_b128 v[194:197], v161 offset:1024
	ds_read_b128 v[198:201], v161 offset:2048
	ds_read_b128 v[202:205], v161 offset:3072
	ds_read_b128 v[206:209], v161 offset:4096
	ds_read_b128 v[210:213], v161 offset:5120
	ds_read_b128 v[214:217], v161 offset:6144
	ds_read_b128 v[218:221], v161 offset:7168
	global_load_lds_dwordx4 v146, s[26:27]
	s_add_i32 m0, s46, 0xe000
	s_nop 0
	global_load_lds_dwordx4 v148, s[26:27]
	s_waitcnt vmcnt(8)
	s_waitcnt lgkmcnt(0)
	s_barrier
	s_waitcnt lgkmcnt(0)
	v_mfma_f32_16x16x32_bf16 v[62:65], v[130:133], v[190:193], v[62:65]
	v_mfma_f32_16x16x32_bf16 v[62:65], v[162:165], v[194:197], v[62:65]
	v_mfma_f32_16x16x32_bf16 v[58:61], v[166:169], v[190:193], v[58:61]
	v_mfma_f32_16x16x32_bf16 v[58:61], v[170:173], v[194:197], v[58:61]
	v_mfma_f32_16x16x32_bf16 v[54:57], v[130:133], v[198:201], v[54:57]
	v_mfma_f32_16x16x32_bf16 v[54:57], v[162:165], v[202:205], v[54:57]
	v_mfma_f32_16x16x32_bf16 v[50:53], v[166:169], v[198:201], v[50:53]
	v_mfma_f32_16x16x32_bf16 v[50:53], v[170:173], v[202:205], v[50:53]
	v_mfma_f32_16x16x32_bf16 v[46:49], v[130:133], v[206:209], v[46:49]
	v_mfma_f32_16x16x32_bf16 v[46:49], v[162:165], v[210:213], v[46:49]
	v_mfma_f32_16x16x32_bf16 v[42:45], v[166:169], v[206:209], v[42:45]
	v_mfma_f32_16x16x32_bf16 v[42:45], v[170:173], v[210:213], v[42:45]
	v_mfma_f32_16x16x32_bf16 v[38:41], v[130:133], v[214:217], v[38:41]
	v_mfma_f32_16x16x32_bf16 v[38:41], v[162:165], v[218:221], v[38:41]
	v_mfma_f32_16x16x32_bf16 v[34:37], v[166:169], v[214:217], v[34:37]
	v_mfma_f32_16x16x32_bf16 v[34:37], v[170:173], v[218:221], v[34:37]
	v_mfma_f32_16x16x32_bf16 v[126:129], v[174:177], v[190:193], v[126:129]
	v_mfma_f32_16x16x32_bf16 v[126:129], v[178:181], v[194:197], v[126:129]
	v_mfma_f32_16x16x32_bf16 v[122:125], v[182:185], v[190:193], v[122:125]
	v_mfma_f32_16x16x32_bf16 v[122:125], v[186:189], v[194:197], v[122:125]
	v_mfma_f32_16x16x32_bf16 v[118:121], v[174:177], v[198:201], v[118:121]
	v_mfma_f32_16x16x32_bf16 v[118:121], v[178:181], v[202:205], v[118:121]
	v_mfma_f32_16x16x32_bf16 v[114:117], v[182:185], v[198:201], v[114:117]
	v_mfma_f32_16x16x32_bf16 v[114:117], v[186:189], v[202:205], v[114:117]
	v_mfma_f32_16x16x32_bf16 v[110:113], v[174:177], v[206:209], v[110:113]
	v_mfma_f32_16x16x32_bf16 v[110:113], v[178:181], v[210:213], v[110:113]
	v_mfma_f32_16x16x32_bf16 v[106:109], v[182:185], v[206:209], v[106:109]
	v_mfma_f32_16x16x32_bf16 v[106:109], v[186:189], v[210:213], v[106:109]
	v_mfma_f32_16x16x32_bf16 v[102:105], v[174:177], v[214:217], v[102:105]
	v_mfma_f32_16x16x32_bf16 v[102:105], v[178:181], v[218:221], v[102:105]
	v_mfma_f32_16x16x32_bf16 v[98:101], v[182:185], v[214:217], v[98:101]
	v_mfma_f32_16x16x32_bf16 v[98:101], v[186:189], v[218:221], v[98:101]
	s_barrier
	s_add_i32 s88, s66, s41
	s_mov_b32 m0, s88
	ds_read_b128 v[190:193], v161 offset:16384
	ds_read_b128 v[194:197], v161 offset:17408
	ds_read_b128 v[198:201], v161 offset:18432
	ds_read_b128 v[202:205], v161 offset:19456
	ds_read_b128 v[206:209], v161 offset:20480
	ds_read_b128 v[210:213], v161 offset:21504
	ds_read_b128 v[214:217], v161 offset:22528
	ds_read_b128 v[218:221], v161 offset:23552
	global_load_lds_dwordx4 v138, s[36:37]
	s_add_i32 m0, s88, 0x2000
	s_add_u32 s88, s36, 0x100000
	s_addc_u32 s89, s37, 0
	s_add_i32 vcc_lo, s67, s41
	global_load_lds_dwordx4 v134, s[36:37]
	s_mov_b32 m0, vcc_lo
	s_nop 0
	global_load_lds_dwordx4 v138, s[88:89]
	s_add_i32 m0, vcc_lo, 0x2000
	s_nop 0
	global_load_lds_dwordx4 v134, s[88:89]
	s_mov_b32 m0, s46
	s_nop 0
	global_load_lds_dwordx4 v140, s[38:39]
	s_mov_b32 m0, s47
	s_nop 0
	global_load_lds_dwordx4 v136, s[38:39]
	s_waitcnt vmcnt(8)
	s_waitcnt lgkmcnt(0)
	s_barrier
	s_waitcnt lgkmcnt(0)
	v_mfma_f32_16x16x32_bf16 v[30:33], v[130:133], v[190:193], v[30:33]
	v_mfma_f32_16x16x32_bf16 v[30:33], v[162:165], v[194:197], v[30:33]
	v_mfma_f32_16x16x32_bf16 v[26:29], v[166:169], v[190:193], v[26:29]
	v_mfma_f32_16x16x32_bf16 v[26:29], v[170:173], v[194:197], v[26:29]
	v_mfma_f32_16x16x32_bf16 v[22:25], v[130:133], v[198:201], v[22:25]
	v_mfma_f32_16x16x32_bf16 v[22:25], v[162:165], v[202:205], v[22:25]
	v_mfma_f32_16x16x32_bf16 v[18:21], v[166:169], v[198:201], v[18:21]
	v_mfma_f32_16x16x32_bf16 v[18:21], v[170:173], v[202:205], v[18:21]
	v_mfma_f32_16x16x32_bf16 v[14:17], v[130:133], v[206:209], v[14:17]
	v_mfma_f32_16x16x32_bf16 v[14:17], v[162:165], v[210:213], v[14:17]
	v_mfma_f32_16x16x32_bf16 v[10:13], v[166:169], v[206:209], v[10:13]
	v_mfma_f32_16x16x32_bf16 v[10:13], v[170:173], v[210:213], v[10:13]
	v_mfma_f32_16x16x32_bf16 v[6:9], v[130:133], v[214:217], v[6:9]
	v_mfma_f32_16x16x32_bf16 v[6:9], v[162:165], v[218:221], v[6:9]
	v_mfma_f32_16x16x32_bf16 v[2:5], v[166:169], v[214:217], v[2:5]
	v_mfma_f32_16x16x32_bf16 v[2:5], v[170:173], v[218:221], v[2:5]
	v_mfma_f32_16x16x32_bf16 v[94:97], v[174:177], v[190:193], v[94:97]
	v_mfma_f32_16x16x32_bf16 v[94:97], v[178:181], v[194:197], v[94:97]
	v_mfma_f32_16x16x32_bf16 v[90:93], v[182:185], v[190:193], v[90:93]
	v_mfma_f32_16x16x32_bf16 v[90:93], v[186:189], v[194:197], v[90:93]
	v_mfma_f32_16x16x32_bf16 v[86:89], v[174:177], v[198:201], v[86:89]
	v_mfma_f32_16x16x32_bf16 v[86:89], v[178:181], v[202:205], v[86:89]
	v_mfma_f32_16x16x32_bf16 v[82:85], v[182:185], v[198:201], v[82:85]
	v_mfma_f32_16x16x32_bf16 v[82:85], v[186:189], v[202:205], v[82:85]
	v_mfma_f32_16x16x32_bf16 v[78:81], v[174:177], v[206:209], v[78:81]
	v_mfma_f32_16x16x32_bf16 v[78:81], v[178:181], v[210:213], v[78:81]
	v_mfma_f32_16x16x32_bf16 v[74:77], v[182:185], v[206:209], v[74:77]
	v_mfma_f32_16x16x32_bf16 v[74:77], v[186:189], v[210:213], v[74:77]
	v_mfma_f32_16x16x32_bf16 v[70:73], v[174:177], v[214:217], v[70:73]
	v_mfma_f32_16x16x32_bf16 v[70:73], v[178:181], v[218:221], v[70:73]
	v_mfma_f32_16x16x32_bf16 v[66:69], v[182:185], v[214:217], v[66:69]
	v_mfma_f32_16x16x32_bf16 v[66:69], v[186:189], v[218:221], v[66:69]
	s_barrier
	s_add_i32 s88, 0, 0x18000
	v_add_u32_e32 v154, s88, v157
	s_add_i32 s89, 0, 0x1c000
	ds_read_b128 v[130:133], v154
	ds_read_b128 v[162:165], v154 offset:1024
	ds_read_b128 v[166:169], v154 offset:2048
	ds_read_b128 v[170:173], v154 offset:3072
	v_add_u32_e32 v154, s89, v157
	ds_read_b128 v[174:177], v154
	ds_read_b128 v[178:181], v154 offset:1024
	ds_read_b128 v[182:185], v154 offset:2048
	ds_read_b128 v[186:189], v154 offset:3072
	s_add_u32 s38, s38, 0x100000
	s_addc_u32 s39, s39, 0
	s_mov_b32 m0, s58
	ds_read_b128 v[190:193], v161 offset:32768
	ds_read_b128 v[194:197], v161 offset:33792
	ds_read_b128 v[198:201], v161 offset:34816
	ds_read_b128 v[202:205], v161 offset:35840
	ds_read_b128 v[206:209], v161 offset:36864
	ds_read_b128 v[210:213], v161 offset:37888
	ds_read_b128 v[214:217], v161 offset:38912
	ds_read_b128 v[218:221], v161 offset:39936
	global_load_lds_dwordx4 v140, s[38:39]
	s_mov_b32 m0, s59
	s_nop 0
	global_load_lds_dwordx4 v136, s[38:39]
	s_waitcnt vmcnt(8)
	s_waitcnt lgkmcnt(0)
	s_barrier
	s_waitcnt lgkmcnt(0)
	v_mfma_f32_16x16x32_bf16 v[62:65], v[130:133], v[190:193], v[62:65]
	v_mfma_f32_16x16x32_bf16 v[62:65], v[162:165], v[194:197], v[62:65]
	v_mfma_f32_16x16x32_bf16 v[58:61], v[166:169], v[190:193], v[58:61]
	v_mfma_f32_16x16x32_bf16 v[58:61], v[170:173], v[194:197], v[58:61]
	v_mfma_f32_16x16x32_bf16 v[54:57], v[130:133], v[198:201], v[54:57]
	v_mfma_f32_16x16x32_bf16 v[54:57], v[162:165], v[202:205], v[54:57]
	v_mfma_f32_16x16x32_bf16 v[50:53], v[166:169], v[198:201], v[50:53]
	v_mfma_f32_16x16x32_bf16 v[50:53], v[170:173], v[202:205], v[50:53]
	v_mfma_f32_16x16x32_bf16 v[46:49], v[130:133], v[206:209], v[46:49]
	v_mfma_f32_16x16x32_bf16 v[46:49], v[162:165], v[210:213], v[46:49]
	v_mfma_f32_16x16x32_bf16 v[42:45], v[166:169], v[206:209], v[42:45]
	v_mfma_f32_16x16x32_bf16 v[42:45], v[170:173], v[210:213], v[42:45]
	v_mfma_f32_16x16x32_bf16 v[38:41], v[130:133], v[214:217], v[38:41]
	v_mfma_f32_16x16x32_bf16 v[38:41], v[162:165], v[218:221], v[38:41]
	v_mfma_f32_16x16x32_bf16 v[34:37], v[166:169], v[214:217], v[34:37]
	v_mfma_f32_16x16x32_bf16 v[34:37], v[170:173], v[218:221], v[34:37]
	v_mfma_f32_16x16x32_bf16 v[126:129], v[174:177], v[190:193], v[126:129]
	v_mfma_f32_16x16x32_bf16 v[126:129], v[178:181], v[194:197], v[126:129]
	v_mfma_f32_16x16x32_bf16 v[122:125], v[182:185], v[190:193], v[122:125]
	v_mfma_f32_16x16x32_bf16 v[122:125], v[186:189], v[194:197], v[122:125]
	v_mfma_f32_16x16x32_bf16 v[118:121], v[174:177], v[198:201], v[118:121]
	v_mfma_f32_16x16x32_bf16 v[118:121], v[178:181], v[202:205], v[118:121]
	v_mfma_f32_16x16x32_bf16 v[114:117], v[182:185], v[198:201], v[114:117]
	v_mfma_f32_16x16x32_bf16 v[114:117], v[186:189], v[202:205], v[114:117]
	v_mfma_f32_16x16x32_bf16 v[110:113], v[174:177], v[206:209], v[110:113]
	v_mfma_f32_16x16x32_bf16 v[110:113], v[178:181], v[210:213], v[110:113]
	v_mfma_f32_16x16x32_bf16 v[106:109], v[182:185], v[206:209], v[106:109]
	v_mfma_f32_16x16x32_bf16 v[106:109], v[186:189], v[210:213], v[106:109]
	v_mfma_f32_16x16x32_bf16 v[102:105], v[174:177], v[214:217], v[102:105]
	v_mfma_f32_16x16x32_bf16 v[102:105], v[178:181], v[218:221], v[102:105]
	v_mfma_f32_16x16x32_bf16 v[98:101], v[182:185], v[214:217], v[98:101]
	v_mfma_f32_16x16x32_bf16 v[98:101], v[186:189], v[218:221], v[98:101]
	s_barrier
	s_add_u32 s38, s36, 0x4000
	s_addc_u32 s39, s37, 0
	s_add_i32 s88, s88, s41
	s_mov_b32 m0, s88
	ds_read_b128 v[190:193], v161 offset:49152
	ds_read_b128 v[194:197], v161 offset:50176
	ds_read_b128 v[198:201], v161 offset:51200
	ds_read_b128 v[202:205], v161 offset:52224
	ds_read_b128 v[206:209], v161 offset:53248
	ds_read_b128 v[210:213], v161 offset:54272
	ds_read_b128 v[214:217], v161 offset:55296
	ds_read_b128 v[218:221], v161 offset:56320
	global_load_lds_dwordx4 v138, s[38:39]
	s_add_i32 m0, s88, 0x2000
	s_add_u32 s36, s36, 0x104000
	s_addc_u32 s37, s37, 0
	global_load_lds_dwordx4 v134, s[38:39]
	s_add_i32 s38, s89, s41
	s_mov_b32 m0, s38
	s_nop 0
	global_load_lds_dwordx4 v138, s[36:37]
	s_add_i32 m0, s38, 0x2000
	s_nop 0
	global_load_lds_dwordx4 v134, s[36:37]
	s_mov_b32 m0, s64
	s_nop 0
	global_load_lds_dwordx4 v140, s[34:35]
	s_mov_b32 m0, s65
	s_nop 0
	global_load_lds_dwordx4 v136, s[34:35]
	s_waitcnt vmcnt(8)
	s_waitcnt lgkmcnt(0)
	s_barrier
	s_waitcnt lgkmcnt(0)
	v_mfma_f32_16x16x32_bf16 v[30:33], v[130:133], v[190:193], v[30:33]
	v_mfma_f32_16x16x32_bf16 v[30:33], v[162:165], v[194:197], v[30:33]
	v_mfma_f32_16x16x32_bf16 v[26:29], v[166:169], v[190:193], v[26:29]
	v_mfma_f32_16x16x32_bf16 v[26:29], v[170:173], v[194:197], v[26:29]
	v_mfma_f32_16x16x32_bf16 v[22:25], v[130:133], v[198:201], v[22:25]
	v_mfma_f32_16x16x32_bf16 v[22:25], v[162:165], v[202:205], v[22:25]
	v_mfma_f32_16x16x32_bf16 v[18:21], v[166:169], v[198:201], v[18:21]
	v_mfma_f32_16x16x32_bf16 v[18:21], v[170:173], v[202:205], v[18:21]
	v_mfma_f32_16x16x32_bf16 v[14:17], v[130:133], v[206:209], v[14:17]
	v_mfma_f32_16x16x32_bf16 v[14:17], v[162:165], v[210:213], v[14:17]
	v_mfma_f32_16x16x32_bf16 v[10:13], v[166:169], v[206:209], v[10:13]
	v_mfma_f32_16x16x32_bf16 v[10:13], v[170:173], v[210:213], v[10:13]
	v_mfma_f32_16x16x32_bf16 v[6:9], v[130:133], v[214:217], v[6:9]
	v_mfma_f32_16x16x32_bf16 v[6:9], v[162:165], v[218:221], v[6:9]
	v_mfma_f32_16x16x32_bf16 v[2:5], v[166:169], v[214:217], v[2:5]
	v_mfma_f32_16x16x32_bf16 v[2:5], v[170:173], v[218:221], v[2:5]
	v_mfma_f32_16x16x32_bf16 v[94:97], v[174:177], v[190:193], v[94:97]
	v_mfma_f32_16x16x32_bf16 v[94:97], v[178:181], v[194:197], v[94:97]
	v_mfma_f32_16x16x32_bf16 v[90:93], v[182:185], v[190:193], v[90:93]
	v_mfma_f32_16x16x32_bf16 v[90:93], v[186:189], v[194:197], v[90:93]
	v_mfma_f32_16x16x32_bf16 v[86:89], v[174:177], v[198:201], v[86:89]
	v_mfma_f32_16x16x32_bf16 v[86:89], v[178:181], v[202:205], v[86:89]
	v_mfma_f32_16x16x32_bf16 v[82:85], v[182:185], v[198:201], v[82:85]
	v_mfma_f32_16x16x32_bf16 v[82:85], v[186:189], v[202:205], v[82:85]
	v_mfma_f32_16x16x32_bf16 v[78:81], v[174:177], v[206:209], v[78:81]
	v_mfma_f32_16x16x32_bf16 v[78:81], v[178:181], v[210:213], v[78:81]
	v_mfma_f32_16x16x32_bf16 v[74:77], v[182:185], v[206:209], v[74:77]
	v_mfma_f32_16x16x32_bf16 v[74:77], v[186:189], v[210:213], v[74:77]
	v_mfma_f32_16x16x32_bf16 v[70:73], v[174:177], v[214:217], v[70:73]
	v_mfma_f32_16x16x32_bf16 v[70:73], v[178:181], v[218:221], v[70:73]
	v_mfma_f32_16x16x32_bf16 v[66:69], v[182:185], v[214:217], v[66:69]
	v_mfma_f32_16x16x32_bf16 v[66:69], v[186:189], v[218:221], v[66:69]
	s_barrier
	s_add_i32 s87, s87, 2
	s_add_u32 s26, s26, 0x8000
	s_addc_u32 s27, s27, 0
	s_add_u32 s83, s83, 0x8000
	s_addc_u32 s86, s86, 0
	s_cmp_gt_u32 s87, 61
	s_cbranch_scc0 .LBB0_376
	s_and_b64 vcc, exec, s[14:15]
	s_cbranch_vccz .LBB0_379
	s_barrier

.LBB0_536:
	ds_read_b128 v[130:133], v159
	ds_read_b128 v[162:165], v159 offset:1024
	ds_read_b128 v[166:169], v159 offset:2048
	ds_read_b128 v[170:173], v159 offset:3072
	ds_read_b128 v[174:177], v160
	ds_read_b128 v[178:181], v160 offset:1024
	ds_read_b128 v[182:185], v160 offset:2048
	ds_read_b128 v[186:189], v160 offset:3072
	s_add_u32 s30, s26, 0xfff04000
	s_addc_u32 s31, s27, -1
	s_cmp_eq_u32 s80, 60
	s_cselect_b32 s36, s74, s30
	s_cselect_b32 s37, s21, s31
	s_cselect_b32 s34, s75, s78
	s_cselect_b32 s35, s19, s79
	s_add_u32 s30, s36, 0x4000
	s_addc_u32 s31, s37, 0
	s_add_i32 m0, s42, 0xc000
	ds_read_b128 v[190:193], v161
	ds_read_b128 v[194:197], v161 offset:1024
	ds_read_b128 v[198:201], v161 offset:2048
	ds_read_b128 v[202:205], v161 offset:3072
	ds_read_b128 v[206:209], v161 offset:4096
	ds_read_b128 v[210:213], v161 offset:5120
	ds_read_b128 v[214:217], v161 offset:6144
	ds_read_b128 v[218:221], v161 offset:7168
	global_load_lds_dwordx4 v146, s[26:27]
	s_add_i32 m0, s42, 0xe000
	s_nop 0
	global_load_lds_dwordx4 v148, s[26:27]
	s_waitcnt vmcnt(8)
	s_waitcnt lgkmcnt(0)
	s_barrier
	s_waitcnt lgkmcnt(0)
	v_mfma_f32_16x16x32_bf16 v[62:65], v[130:133], v[190:193], v[62:65]
	v_mfma_f32_16x16x32_bf16 v[62:65], v[162:165], v[194:197], v[62:65]
	v_mfma_f32_16x16x32_bf16 v[58:61], v[166:169], v[190:193], v[58:61]
	v_mfma_f32_16x16x32_bf16 v[58:61], v[170:173], v[194:197], v[58:61]
	v_mfma_f32_16x16x32_bf16 v[54:57], v[130:133], v[198:201], v[54:57]
	v_mfma_f32_16x16x32_bf16 v[54:57], v[162:165], v[202:205], v[54:57]
	v_mfma_f32_16x16x32_bf16 v[50:53], v[166:169], v[198:201], v[50:53]
	v_mfma_f32_16x16x32_bf16 v[50:53], v[170:173], v[202:205], v[50:53]
	v_mfma_f32_16x16x32_bf16 v[46:49], v[130:133], v[206:209], v[46:49]
	v_mfma_f32_16x16x32_bf16 v[46:49], v[162:165], v[210:213], v[46:49]
	v_mfma_f32_16x16x32_bf16 v[42:45], v[166:169], v[206:209], v[42:45]
	v_mfma_f32_16x16x32_bf16 v[42:45], v[170:173], v[210:213], v[42:45]
	v_mfma_f32_16x16x32_bf16 v[38:41], v[130:133], v[214:217], v[38:41]
	v_mfma_f32_16x16x32_bf16 v[38:41], v[162:165], v[218:221], v[38:41]
	v_mfma_f32_16x16x32_bf16 v[34:37], v[166:169], v[214:217], v[34:37]
	v_mfma_f32_16x16x32_bf16 v[34:37], v[170:173], v[218:221], v[34:37]
	v_mfma_f32_16x16x32_bf16 v[126:129], v[174:177], v[190:193], v[126:129]
	v_mfma_f32_16x16x32_bf16 v[126:129], v[178:181], v[194:197], v[126:129]
	v_mfma_f32_16x16x32_bf16 v[122:125], v[182:185], v[190:193], v[122:125]
	v_mfma_f32_16x16x32_bf16 v[122:125], v[186:189], v[194:197], v[122:125]
	v_mfma_f32_16x16x32_bf16 v[118:121], v[174:177], v[198:201], v[118:121]
	v_mfma_f32_16x16x32_bf16 v[118:121], v[178:181], v[202:205], v[118:121]
	v_mfma_f32_16x16x32_bf16 v[114:117], v[182:185], v[198:201], v[114:117]
	v_mfma_f32_16x16x32_bf16 v[114:117], v[186:189], v[202:205], v[114:117]
	v_mfma_f32_16x16x32_bf16 v[110:113], v[174:177], v[206:209], v[110:113]
	v_mfma_f32_16x16x32_bf16 v[110:113], v[178:181], v[210:213], v[110:113]
	v_mfma_f32_16x16x32_bf16 v[106:109], v[182:185], v[206:209], v[106:109]
	v_mfma_f32_16x16x32_bf16 v[106:109], v[186:189], v[210:213], v[106:109]
	v_mfma_f32_16x16x32_bf16 v[102:105], v[174:177], v[214:217], v[102:105]
	v_mfma_f32_16x16x32_bf16 v[102:105], v[178:181], v[218:221], v[102:105]
	v_mfma_f32_16x16x32_bf16 v[98:101], v[182:185], v[214:217], v[98:101]
	v_mfma_f32_16x16x32_bf16 v[98:101], v[186:189], v[218:221], v[98:101]
	s_barrier
	s_add_i32 s81, s62, s38
	s_mov_b32 m0, s81
	ds_read_b128 v[190:193], v161 offset:16384
	ds_read_b128 v[194:197], v161 offset:17408
	ds_read_b128 v[198:201], v161 offset:18432
	ds_read_b128 v[202:205], v161 offset:19456
	ds_read_b128 v[206:209], v161 offset:20480
	ds_read_b128 v[210:213], v161 offset:21504
	ds_read_b128 v[214:217], v161 offset:22528
	ds_read_b128 v[218:221], v161 offset:23552
	global_load_lds_dwordx4 v138, s[34:35]
	s_add_i32 m0, s81, 0x2000
	s_add_u32 s86, s34, 0x100000
	s_addc_u32 s87, s35, 0
	s_add_i32 s81, s63, s38
	global_load_lds_dwordx4 v134, s[34:35]
	s_mov_b32 m0, s81
	s_nop 0
	global_load_lds_dwordx4 v138, s[86:87]
	s_add_i32 m0, s81, 0x2000
	s_nop 0
	global_load_lds_dwordx4 v134, s[86:87]
	s_mov_b32 m0, s42
	s_nop 0
	global_load_lds_dwordx4 v140, s[36:37]
	s_mov_b32 m0, s43
	s_nop 0
	global_load_lds_dwordx4 v136, s[36:37]
	s_waitcnt vmcnt(8)
	s_waitcnt lgkmcnt(0)
	s_barrier
	s_waitcnt lgkmcnt(0)
	v_mfma_f32_16x16x32_bf16 v[30:33], v[130:133], v[190:193], v[30:33]
	v_mfma_f32_16x16x32_bf16 v[30:33], v[162:165], v[194:197], v[30:33]
	v_mfma_f32_16x16x32_bf16 v[26:29], v[166:169], v[190:193], v[26:29]
	v_mfma_f32_16x16x32_bf16 v[26:29], v[170:173], v[194:197], v[26:29]
	v_mfma_f32_16x16x32_bf16 v[22:25], v[130:133], v[198:201], v[22:25]
	v_mfma_f32_16x16x32_bf16 v[22:25], v[162:165], v[202:205], v[22:25]
	v_mfma_f32_16x16x32_bf16 v[18:21], v[166:169], v[198:201], v[18:21]
	v_mfma_f32_16x16x32_bf16 v[18:21], v[170:173], v[202:205], v[18:21]
	v_mfma_f32_16x16x32_bf16 v[14:17], v[130:133], v[206:209], v[14:17]
	v_mfma_f32_16x16x32_bf16 v[14:17], v[162:165], v[210:213], v[14:17]
	v_mfma_f32_16x16x32_bf16 v[10:13], v[166:169], v[206:209], v[10:13]
	v_mfma_f32_16x16x32_bf16 v[10:13], v[170:173], v[210:213], v[10:13]
	v_mfma_f32_16x16x32_bf16 v[6:9], v[130:133], v[214:217], v[6:9]
	v_mfma_f32_16x16x32_bf16 v[6:9], v[162:165], v[218:221], v[6:9]
	v_mfma_f32_16x16x32_bf16 v[2:5], v[166:169], v[214:217], v[2:5]
	v_mfma_f32_16x16x32_bf16 v[2:5], v[170:173], v[218:221], v[2:5]
	v_mfma_f32_16x16x32_bf16 v[94:97], v[174:177], v[190:193], v[94:97]
	v_mfma_f32_16x16x32_bf16 v[94:97], v[178:181], v[194:197], v[94:97]
	v_mfma_f32_16x16x32_bf16 v[90:93], v[182:185], v[190:193], v[90:93]
	v_mfma_f32_16x16x32_bf16 v[90:93], v[186:189], v[194:197], v[90:93]
	v_mfma_f32_16x16x32_bf16 v[86:89], v[174:177], v[198:201], v[86:89]
	v_mfma_f32_16x16x32_bf16 v[86:89], v[178:181], v[202:205], v[86:89]
	v_mfma_f32_16x16x32_bf16 v[82:85], v[182:185], v[198:201], v[82:85]
	v_mfma_f32_16x16x32_bf16 v[82:85], v[186:189], v[202:205], v[82:85]
	v_mfma_f32_16x16x32_bf16 v[78:81], v[174:177], v[206:209], v[78:81]
	v_mfma_f32_16x16x32_bf16 v[78:81], v[178:181], v[210:213], v[78:81]
	v_mfma_f32_16x16x32_bf16 v[74:77], v[182:185], v[206:209], v[74:77]
	v_mfma_f32_16x16x32_bf16 v[74:77], v[186:189], v[210:213], v[74:77]
	v_mfma_f32_16x16x32_bf16 v[70:73], v[174:177], v[214:217], v[70:73]
	v_mfma_f32_16x16x32_bf16 v[70:73], v[178:181], v[218:221], v[70:73]
	v_mfma_f32_16x16x32_bf16 v[66:69], v[182:185], v[214:217], v[66:69]
	v_mfma_f32_16x16x32_bf16 v[66:69], v[186:189], v[218:221], v[66:69]
	s_barrier
	s_add_i32 s81, 0, 0x18000
	v_add_u32_e32 v154, s81, v157
	s_add_i32 s83, 0, 0x1c000
	ds_read_b128 v[130:133], v154
	ds_read_b128 v[162:165], v154 offset:1024
	ds_read_b128 v[166:169], v154 offset:2048
	ds_read_b128 v[170:173], v154 offset:3072
	v_add_u32_e32 v154, s83, v157
	ds_read_b128 v[174:177], v154
	ds_read_b128 v[178:181], v154 offset:1024
	ds_read_b128 v[182:185], v154 offset:2048
	ds_read_b128 v[186:189], v154 offset:3072
	s_add_u32 s36, s36, 0x100000
	s_addc_u32 s37, s37, 0
	s_mov_b32 m0, s46
	ds_read_b128 v[190:193], v161 offset:32768
	ds_read_b128 v[194:197], v161 offset:33792
	ds_read_b128 v[198:201], v161 offset:34816
	ds_read_b128 v[202:205], v161 offset:35840
	ds_read_b128 v[206:209], v161 offset:36864
	ds_read_b128 v[210:213], v161 offset:37888
	ds_read_b128 v[214:217], v161 offset:38912
	ds_read_b128 v[218:221], v161 offset:39936
	global_load_lds_dwordx4 v140, s[36:37]
	s_mov_b32 m0, s47
	s_nop 0
	global_load_lds_dwordx4 v136, s[36:37]
	s_waitcnt vmcnt(8)
	s_waitcnt lgkmcnt(0)
	s_barrier
	s_waitcnt lgkmcnt(0)
	v_mfma_f32_16x16x32_bf16 v[62:65], v[130:133], v[190:193], v[62:65]
	v_mfma_f32_16x16x32_bf16 v[62:65], v[162:165], v[194:197], v[62:65]
	v_mfma_f32_16x16x32_bf16 v[58:61], v[166:169], v[190:193], v[58:61]
	v_mfma_f32_16x16x32_bf16 v[58:61], v[170:173], v[194:197], v[58:61]
	v_mfma_f32_16x16x32_bf16 v[54:57], v[130:133], v[198:201], v[54:57]
	v_mfma_f32_16x16x32_bf16 v[54:57], v[162:165], v[202:205], v[54:57]
	v_mfma_f32_16x16x32_bf16 v[50:53], v[166:169], v[198:201], v[50:53]
	v_mfma_f32_16x16x32_bf16 v[50:53], v[170:173], v[202:205], v[50:53]
	v_mfma_f32_16x16x32_bf16 v[46:49], v[130:133], v[206:209], v[46:49]
	v_mfma_f32_16x16x32_bf16 v[46:49], v[162:165], v[210:213], v[46:49]
	v_mfma_f32_16x16x32_bf16 v[42:45], v[166:169], v[206:209], v[42:45]
	v_mfma_f32_16x16x32_bf16 v[42:45], v[170:173], v[210:213], v[42:45]
	v_mfma_f32_16x16x32_bf16 v[38:41], v[130:133], v[214:217], v[38:41]
	v_mfma_f32_16x16x32_bf16 v[38:41], v[162:165], v[218:221], v[38:41]
	v_mfma_f32_16x16x32_bf16 v[34:37], v[166:169], v[214:217], v[34:37]
	v_mfma_f32_16x16x32_bf16 v[34:37], v[170:173], v[218:221], v[34:37]
	v_mfma_f32_16x16x32_bf16 v[126:129], v[174:177], v[190:193], v[126:129]
	v_mfma_f32_16x16x32_bf16 v[126:129], v[178:181], v[194:197], v[126:129]
	v_mfma_f32_16x16x32_bf16 v[122:125], v[182:185], v[190:193], v[122:125]
	v_mfma_f32_16x16x32_bf16 v[122:125], v[186:189], v[194:197], v[122:125]
	v_mfma_f32_16x16x32_bf16 v[118:121], v[174:177], v[198:201], v[118:121]
	v_mfma_f32_16x16x32_bf16 v[118:121], v[178:181], v[202:205], v[118:121]
	v_mfma_f32_16x16x32_bf16 v[114:117], v[182:185], v[198:201], v[114:117]
	v_mfma_f32_16x16x32_bf16 v[114:117], v[186:189], v[202:205], v[114:117]
	v_mfma_f32_16x16x32_bf16 v[110:113], v[174:177], v[206:209], v[110:113]
	v_mfma_f32_16x16x32_bf16 v[110:113], v[178:181], v[210:213], v[110:113]
	v_mfma_f32_16x16x32_bf16 v[106:109], v[182:185], v[206:209], v[106:109]
	v_mfma_f32_16x16x32_bf16 v[106:109], v[186:189], v[210:213], v[106:109]
	v_mfma_f32_16x16x32_bf16 v[102:105], v[174:177], v[214:217], v[102:105]
	v_mfma_f32_16x16x32_bf16 v[102:105], v[178:181], v[218:221], v[102:105]
	v_mfma_f32_16x16x32_bf16 v[98:101], v[182:185], v[214:217], v[98:101]
	v_mfma_f32_16x16x32_bf16 v[98:101], v[186:189], v[218:221], v[98:101]
	s_barrier
	s_add_u32 s36, s34, 0x4000
	s_addc_u32 s37, s35, 0
	s_add_i32 s81, s81, s38
	s_mov_b32 m0, s81
	ds_read_b128 v[190:193], v161 offset:49152
	ds_read_b128 v[194:197], v161 offset:50176
	ds_read_b128 v[198:201], v161 offset:51200
	ds_read_b128 v[202:205], v161 offset:52224
	ds_read_b128 v[206:209], v161 offset:53248
	ds_read_b128 v[210:213], v161 offset:54272
	ds_read_b128 v[214:217], v161 offset:55296
	ds_read_b128 v[218:221], v161 offset:56320
	global_load_lds_dwordx4 v138, s[36:37]
	s_add_i32 m0, s81, 0x2000
	s_add_u32 s34, s34, 0x104000
	s_addc_u32 s35, s35, 0
	global_load_lds_dwordx4 v134, s[36:37]
	s_add_i32 s36, s83, s38
	s_mov_b32 m0, s36
	s_nop 0
	global_load_lds_dwordx4 v138, s[34:35]
	s_add_i32 m0, s36, 0x2000
	s_nop 0
	global_load_lds_dwordx4 v134, s[34:35]
	s_mov_b32 m0, s58
	s_nop 0
	global_load_lds_dwordx4 v140, s[30:31]
	s_mov_b32 m0, s59
	s_nop 0
	global_load_lds_dwordx4 v136, s[30:31]
	s_waitcnt vmcnt(8)
	s_waitcnt lgkmcnt(0)
	s_barrier
	s_waitcnt lgkmcnt(0)
	v_mfma_f32_16x16x32_bf16 v[30:33], v[130:133], v[190:193], v[30:33]
	v_mfma_f32_16x16x32_bf16 v[30:33], v[162:165], v[194:197], v[30:33]
	v_mfma_f32_16x16x32_bf16 v[26:29], v[166:169], v[190:193], v[26:29]
	v_mfma_f32_16x16x32_bf16 v[26:29], v[170:173], v[194:197], v[26:29]
	v_mfma_f32_16x16x32_bf16 v[22:25], v[130:133], v[198:201], v[22:25]
	v_mfma_f32_16x16x32_bf16 v[22:25], v[162:165], v[202:205], v[22:25]
	v_mfma_f32_16x16x32_bf16 v[18:21], v[166:169], v[198:201], v[18:21]
	v_mfma_f32_16x16x32_bf16 v[18:21], v[170:173], v[202:205], v[18:21]
	v_mfma_f32_16x16x32_bf16 v[14:17], v[130:133], v[206:209], v[14:17]
	v_mfma_f32_16x16x32_bf16 v[14:17], v[162:165], v[210:213], v[14:17]
	v_mfma_f32_16x16x32_bf16 v[10:13], v[166:169], v[206:209], v[10:13]
	v_mfma_f32_16x16x32_bf16 v[10:13], v[170:173], v[210:213], v[10:13]
	v_mfma_f32_16x16x32_bf16 v[6:9], v[130:133], v[214:217], v[6:9]
	v_mfma_f32_16x16x32_bf16 v[6:9], v[162:165], v[218:221], v[6:9]
	v_mfma_f32_16x16x32_bf16 v[2:5], v[166:169], v[214:217], v[2:5]
	v_mfma_f32_16x16x32_bf16 v[2:5], v[170:173], v[218:221], v[2:5]
	v_mfma_f32_16x16x32_bf16 v[94:97], v[174:177], v[190:193], v[94:97]
	v_mfma_f32_16x16x32_bf16 v[94:97], v[178:181], v[194:197], v[94:97]
	v_mfma_f32_16x16x32_bf16 v[90:93], v[182:185], v[190:193], v[90:93]
	v_mfma_f32_16x16x32_bf16 v[90:93], v[186:189], v[194:197], v[90:93]
	v_mfma_f32_16x16x32_bf16 v[86:89], v[174:177], v[198:201], v[86:89]
	v_mfma_f32_16x16x32_bf16 v[86:89], v[178:181], v[202:205], v[86:89]
	v_mfma_f32_16x16x32_bf16 v[82:85], v[182:185], v[198:201], v[82:85]
	v_mfma_f32_16x16x32_bf16 v[82:85], v[186:189], v[202:205], v[82:85]
	v_mfma_f32_16x16x32_bf16 v[78:81], v[174:177], v[206:209], v[78:81]
	v_mfma_f32_16x16x32_bf16 v[78:81], v[178:181], v[210:213], v[78:81]
	v_mfma_f32_16x16x32_bf16 v[74:77], v[182:185], v[206:209], v[74:77]
	v_mfma_f32_16x16x32_bf16 v[74:77], v[186:189], v[210:213], v[74:77]
	v_mfma_f32_16x16x32_bf16 v[70:73], v[174:177], v[214:217], v[70:73]
	v_mfma_f32_16x16x32_bf16 v[70:73], v[178:181], v[218:221], v[70:73]
	v_mfma_f32_16x16x32_bf16 v[66:69], v[182:185], v[214:217], v[66:69]
	v_mfma_f32_16x16x32_bf16 v[66:69], v[186:189], v[218:221], v[66:69]
	s_barrier
	s_add_i32 s80, s80, 2
	s_add_u32 s26, s26, 0x8000
	s_addc_u32 s27, s27, 0
	s_add_u32 s78, s78, 0x8000
	s_addc_u32 s79, s79, 0
	s_cmp_gt_u32 s80, 61
	s_cbranch_scc0 .LBB0_536
	s_and_b64 vcc, exec, s[14:15]
	s_cbranch_vccz .LBB0_539
	s_barrier

.LBB0_1005:
	v_add_u32_e32 v142, s46, v200
	v_add_u32_e32 v158, s47, v200
	ds_read_b128 v[130:133], v142
	ds_read_b128 v[134:137], v142 offset:1024
	ds_read_b128 v[138:141], v142 offset:2048
	ds_read_b128 v[142:145], v142 offset:3072
	ds_read_b128 v[146:149], v158
	ds_read_b128 v[150:153], v158 offset:1024
	ds_read_b128 v[154:157], v158 offset:2048
	ds_read_b128 v[158:161], v158 offset:3072
	s_add_i32 s70, s31, 2
	s_add_u32 s26, s24, 0xfff44000
	s_addc_u32 s27, s25, -1
	s_cmp_eq_u32 s67, s31
	s_cselect_b32 s34, s6, s26
	s_cselect_b32 s35, s7, s27
	s_cselect_b32 s30, s20, s68
	s_cselect_b32 s31, s21, s69
	s_add_u32 s26, s34, 0x4000
	s_addc_u32 s27, s35, 0
	s_add_i32 m0, s37, 0xc000
	ds_read_b128 v[162:165], v201
	ds_read_b128 v[166:169], v201 offset:1024
	ds_read_b128 v[170:173], v201 offset:2048
	ds_read_b128 v[174:177], v201 offset:3072
	ds_read_b128 v[202:205], v201 offset:4096
	ds_read_b128 v[206:209], v201 offset:5120
	ds_read_b128 v[210:213], v201 offset:6144
	ds_read_b128 v[214:217], v201 offset:7168
	global_load_lds_dwordx4 v190, s[24:25]
	s_add_i32 m0, s37, 0xe000
	s_nop 0
	global_load_lds_dwordx4 v192, s[24:25]
	s_waitcnt vmcnt(8)
	s_waitcnt lgkmcnt(0)
	s_barrier
	s_waitcnt lgkmcnt(0)
	v_mfma_f32_16x16x32_bf16 v[126:129], v[130:133], v[162:165], v[126:129]
	v_mfma_f32_16x16x32_bf16 v[126:129], v[134:137], v[166:169], v[126:129]
	v_mfma_f32_16x16x32_bf16 v[122:125], v[138:141], v[162:165], v[122:125]
	v_mfma_f32_16x16x32_bf16 v[122:125], v[142:145], v[166:169], v[122:125]
	v_mfma_f32_16x16x32_bf16 v[118:121], v[130:133], v[170:173], v[118:121]
	v_mfma_f32_16x16x32_bf16 v[118:121], v[134:137], v[174:177], v[118:121]
	v_mfma_f32_16x16x32_bf16 v[114:117], v[138:141], v[170:173], v[114:117]
	v_mfma_f32_16x16x32_bf16 v[114:117], v[142:145], v[174:177], v[114:117]
	v_mfma_f32_16x16x32_bf16 v[110:113], v[130:133], v[202:205], v[110:113]
	v_mfma_f32_16x16x32_bf16 v[110:113], v[134:137], v[206:209], v[110:113]
	v_mfma_f32_16x16x32_bf16 v[106:109], v[138:141], v[202:205], v[106:109]
	v_mfma_f32_16x16x32_bf16 v[106:109], v[142:145], v[206:209], v[106:109]
	v_mfma_f32_16x16x32_bf16 v[102:105], v[130:133], v[210:213], v[102:105]
	v_mfma_f32_16x16x32_bf16 v[102:105], v[134:137], v[214:217], v[102:105]
	v_mfma_f32_16x16x32_bf16 v[98:101], v[138:141], v[210:213], v[98:101]
	v_mfma_f32_16x16x32_bf16 v[98:101], v[142:145], v[214:217], v[98:101]
	v_mfma_f32_16x16x32_bf16 v[94:97], v[146:149], v[162:165], v[94:97]
	v_mfma_f32_16x16x32_bf16 v[94:97], v[150:153], v[166:169], v[94:97]
	v_mfma_f32_16x16x32_bf16 v[90:93], v[154:157], v[162:165], v[90:93]
	v_mfma_f32_16x16x32_bf16 v[90:93], v[158:161], v[166:169], v[90:93]
	v_mfma_f32_16x16x32_bf16 v[86:89], v[146:149], v[170:173], v[86:89]
	v_mfma_f32_16x16x32_bf16 v[86:89], v[150:153], v[174:177], v[86:89]
	v_mfma_f32_16x16x32_bf16 v[82:85], v[154:157], v[170:173], v[82:85]
	v_mfma_f32_16x16x32_bf16 v[82:85], v[158:161], v[174:177], v[82:85]
	v_mfma_f32_16x16x32_bf16 v[78:81], v[146:149], v[202:205], v[78:81]
	v_mfma_f32_16x16x32_bf16 v[78:81], v[150:153], v[206:209], v[78:81]
	v_mfma_f32_16x16x32_bf16 v[74:77], v[154:157], v[202:205], v[74:77]
	v_mfma_f32_16x16x32_bf16 v[74:77], v[158:161], v[206:209], v[74:77]
	v_mfma_f32_16x16x32_bf16 v[66:69], v[146:149], v[210:213], v[66:69]
	v_mfma_f32_16x16x32_bf16 v[66:69], v[150:153], v[214:217], v[66:69]
	v_mfma_f32_16x16x32_bf16 v[58:61], v[154:157], v[210:213], v[58:61]
	v_mfma_f32_16x16x32_bf16 v[58:61], v[158:161], v[214:217], v[58:61]
	s_barrier
	s_add_i32 s71, s46, s36
	s_mov_b32 m0, s71
	ds_read_b128 v[162:165], v201 offset:16384
	ds_read_b128 v[166:169], v201 offset:17408
	ds_read_b128 v[170:173], v201 offset:18432
	ds_read_b128 v[174:177], v201 offset:19456
	ds_read_b128 v[202:205], v201 offset:20480
	ds_read_b128 v[206:209], v201 offset:21504
	ds_read_b128 v[210:213], v201 offset:22528
	ds_read_b128 v[214:217], v201 offset:23552
	global_load_lds_dwordx4 v182, s[30:31]
	s_add_i32 m0, s71, 0x2000
	s_add_u32 s72, s30, 0xc0000
	s_addc_u32 s73, s31, 0
	s_add_i32 s71, s47, s36
	global_load_lds_dwordx4 v178, s[30:31]
	s_mov_b32 m0, s71
	s_nop 0
	global_load_lds_dwordx4 v182, s[72:73]
	s_add_i32 m0, s71, 0x2000
	s_nop 0
	global_load_lds_dwordx4 v178, s[72:73]
	s_mov_b32 m0, s37
	s_nop 0
	global_load_lds_dwordx4 v184, s[34:35]
	s_mov_b32 m0, s38
	s_nop 0
	global_load_lds_dwordx4 v180, s[34:35]
	s_waitcnt vmcnt(8)
	s_waitcnt lgkmcnt(0)
	s_barrier
	s_waitcnt lgkmcnt(0)
	v_mfma_f32_16x16x32_bf16 v[70:73], v[130:133], v[162:165], v[70:73]
	v_mfma_f32_16x16x32_bf16 v[70:73], v[134:137], v[166:169], v[70:73]
	v_mfma_f32_16x16x32_bf16 v[62:65], v[138:141], v[162:165], v[62:65]
	v_mfma_f32_16x16x32_bf16 v[62:65], v[142:145], v[166:169], v[62:65]
	v_mfma_f32_16x16x32_bf16 v[54:57], v[130:133], v[170:173], v[54:57]
	v_mfma_f32_16x16x32_bf16 v[54:57], v[134:137], v[174:177], v[54:57]
	v_mfma_f32_16x16x32_bf16 v[50:53], v[138:141], v[170:173], v[50:53]
	v_mfma_f32_16x16x32_bf16 v[50:53], v[142:145], v[174:177], v[50:53]
	v_mfma_f32_16x16x32_bf16 v[46:49], v[130:133], v[202:205], v[46:49]
	v_mfma_f32_16x16x32_bf16 v[46:49], v[134:137], v[206:209], v[46:49]
	v_mfma_f32_16x16x32_bf16 v[42:45], v[138:141], v[202:205], v[42:45]
	v_mfma_f32_16x16x32_bf16 v[42:45], v[142:145], v[206:209], v[42:45]
	v_mfma_f32_16x16x32_bf16 v[38:41], v[130:133], v[210:213], v[38:41]
	v_mfma_f32_16x16x32_bf16 v[38:41], v[134:137], v[214:217], v[38:41]
	v_mfma_f32_16x16x32_bf16 v[34:37], v[138:141], v[210:213], v[34:37]
	v_mfma_f32_16x16x32_bf16 v[34:37], v[142:145], v[214:217], v[34:37]
	v_mfma_f32_16x16x32_bf16 v[30:33], v[146:149], v[162:165], v[30:33]
	v_mfma_f32_16x16x32_bf16 v[30:33], v[150:153], v[166:169], v[30:33]
	v_mfma_f32_16x16x32_bf16 v[26:29], v[154:157], v[162:165], v[26:29]
	v_mfma_f32_16x16x32_bf16 v[26:29], v[158:161], v[166:169], v[26:29]
	v_mfma_f32_16x16x32_bf16 v[22:25], v[146:149], v[170:173], v[22:25]
	v_mfma_f32_16x16x32_bf16 v[22:25], v[150:153], v[174:177], v[22:25]
	v_mfma_f32_16x16x32_bf16 v[18:21], v[154:157], v[170:173], v[18:21]
	v_mfma_f32_16x16x32_bf16 v[18:21], v[158:161], v[174:177], v[18:21]
	v_mfma_f32_16x16x32_bf16 v[14:17], v[146:149], v[202:205], v[14:17]
	v_mfma_f32_16x16x32_bf16 v[14:17], v[150:153], v[206:209], v[14:17]
	v_mfma_f32_16x16x32_bf16 v[10:13], v[154:157], v[202:205], v[10:13]
	v_mfma_f32_16x16x32_bf16 v[10:13], v[158:161], v[206:209], v[10:13]
	v_mfma_f32_16x16x32_bf16 v[6:9], v[146:149], v[210:213], v[6:9]
	v_mfma_f32_16x16x32_bf16 v[6:9], v[150:153], v[214:217], v[6:9]
	v_mfma_f32_16x16x32_bf16 v[2:5], v[154:157], v[210:213], v[2:5]
	v_mfma_f32_16x16x32_bf16 v[2:5], v[158:161], v[214:217], v[2:5]
	s_barrier
	s_add_i32 s71, 0, 0x18000
	s_add_i32 s72, 0, 0x1c000
	v_add_u32_e32 v142, s71, v200
	v_add_u32_e32 v158, s72, v200
	ds_read_b128 v[130:133], v142
	ds_read_b128 v[134:137], v142 offset:1024
	ds_read_b128 v[138:141], v142 offset:2048
	ds_read_b128 v[142:145], v142 offset:3072
	ds_read_b128 v[146:149], v158
	ds_read_b128 v[150:153], v158 offset:1024
	ds_read_b128 v[154:157], v158 offset:2048
	ds_read_b128 v[158:161], v158 offset:3072
	s_add_u32 s34, s34, 0xc0000
	s_addc_u32 s35, s35, 0
	s_mov_b32 m0, s39
	ds_read_b128 v[162:165], v201 offset:32768
	ds_read_b128 v[166:169], v201 offset:33792
	ds_read_b128 v[170:173], v201 offset:34816
	ds_read_b128 v[174:177], v201 offset:35840
	ds_read_b128 v[202:205], v201 offset:36864
	ds_read_b128 v[206:209], v201 offset:37888
	ds_read_b128 v[210:213], v201 offset:38912
	ds_read_b128 v[214:217], v201 offset:39936
	global_load_lds_dwordx4 v184, s[34:35]
	s_mov_b32 m0, s40
	s_nop 0
	global_load_lds_dwordx4 v180, s[34:35]
	s_waitcnt vmcnt(8)
	s_waitcnt lgkmcnt(0)
	s_barrier
	s_waitcnt lgkmcnt(0)
	v_mfma_f32_16x16x32_bf16 v[126:129], v[130:133], v[162:165], v[126:129]
	v_mfma_f32_16x16x32_bf16 v[126:129], v[134:137], v[166:169], v[126:129]
	v_mfma_f32_16x16x32_bf16 v[122:125], v[138:141], v[162:165], v[122:125]
	v_mfma_f32_16x16x32_bf16 v[122:125], v[142:145], v[166:169], v[122:125]
	v_mfma_f32_16x16x32_bf16 v[118:121], v[130:133], v[170:173], v[118:121]
	v_mfma_f32_16x16x32_bf16 v[118:121], v[134:137], v[174:177], v[118:121]
	v_mfma_f32_16x16x32_bf16 v[114:117], v[138:141], v[170:173], v[114:117]
	v_mfma_f32_16x16x32_bf16 v[114:117], v[142:145], v[174:177], v[114:117]
	v_mfma_f32_16x16x32_bf16 v[110:113], v[130:133], v[202:205], v[110:113]
	v_mfma_f32_16x16x32_bf16 v[110:113], v[134:137], v[206:209], v[110:113]
	v_mfma_f32_16x16x32_bf16 v[106:109], v[138:141], v[202:205], v[106:109]
	v_mfma_f32_16x16x32_bf16 v[106:109], v[142:145], v[206:209], v[106:109]
	v_mfma_f32_16x16x32_bf16 v[102:105], v[130:133], v[210:213], v[102:105]
	v_mfma_f32_16x16x32_bf16 v[102:105], v[134:137], v[214:217], v[102:105]
	v_mfma_f32_16x16x32_bf16 v[98:101], v[138:141], v[210:213], v[98:101]
	v_mfma_f32_16x16x32_bf16 v[98:101], v[142:145], v[214:217], v[98:101]
	v_mfma_f32_16x16x32_bf16 v[94:97], v[146:149], v[162:165], v[94:97]
	v_mfma_f32_16x16x32_bf16 v[94:97], v[150:153], v[166:169], v[94:97]
	v_mfma_f32_16x16x32_bf16 v[90:93], v[154:157], v[162:165], v[90:93]
	v_mfma_f32_16x16x32_bf16 v[90:93], v[158:161], v[166:169], v[90:93]
	v_mfma_f32_16x16x32_bf16 v[86:89], v[146:149], v[170:173], v[86:89]
	v_mfma_f32_16x16x32_bf16 v[86:89], v[150:153], v[174:177], v[86:89]
	v_mfma_f32_16x16x32_bf16 v[82:85], v[154:157], v[170:173], v[82:85]
	v_mfma_f32_16x16x32_bf16 v[82:85], v[158:161], v[174:177], v[82:85]
	v_mfma_f32_16x16x32_bf16 v[78:81], v[146:149], v[202:205], v[78:81]
	v_mfma_f32_16x16x32_bf16 v[78:81], v[150:153], v[206:209], v[78:81]
	v_mfma_f32_16x16x32_bf16 v[74:77], v[154:157], v[202:205], v[74:77]
	v_mfma_f32_16x16x32_bf16 v[74:77], v[158:161], v[206:209], v[74:77]
	v_mfma_f32_16x16x32_bf16 v[66:69], v[146:149], v[210:213], v[66:69]
	v_mfma_f32_16x16x32_bf16 v[66:69], v[150:153], v[214:217], v[66:69]
	v_mfma_f32_16x16x32_bf16 v[58:61], v[154:157], v[210:213], v[58:61]
	v_mfma_f32_16x16x32_bf16 v[58:61], v[158:161], v[214:217], v[58:61]
	s_barrier
	s_add_u32 s34, s30, 0x4000
	s_addc_u32 s35, s31, 0
	s_add_i32 s71, s71, s36
	s_mov_b32 m0, s71
	ds_read_b128 v[162:165], v201 offset:49152
	ds_read_b128 v[166:169], v201 offset:50176
	ds_read_b128 v[170:173], v201 offset:51200
	ds_read_b128 v[174:177], v201 offset:52224
	ds_read_b128 v[202:205], v201 offset:53248
	ds_read_b128 v[206:209], v201 offset:54272
	ds_read_b128 v[210:213], v201 offset:55296
	ds_read_b128 v[214:217], v201 offset:56320
	global_load_lds_dwordx4 v182, s[34:35]
	s_add_i32 m0, s71, 0x2000
	s_add_u32 s30, s30, 0xc4000
	s_addc_u32 s31, s31, 0
	global_load_lds_dwordx4 v178, s[34:35]
	s_add_i32 s34, s72, s36
	s_mov_b32 m0, s34
	s_nop 0
	global_load_lds_dwordx4 v182, s[30:31]
	s_add_i32 m0, s34, 0x2000
	s_nop 0
	global_load_lds_dwordx4 v178, s[30:31]
	s_mov_b32 m0, s42
	s_nop 0
	global_load_lds_dwordx4 v184, s[26:27]
	s_mov_b32 m0, s43
	s_nop 0
	global_load_lds_dwordx4 v180, s[26:27]
	s_waitcnt vmcnt(8)
	s_waitcnt lgkmcnt(0)
	s_barrier
	s_waitcnt lgkmcnt(0)
	v_mfma_f32_16x16x32_bf16 v[70:73], v[130:133], v[162:165], v[70:73]
	v_mfma_f32_16x16x32_bf16 v[70:73], v[134:137], v[166:169], v[70:73]
	v_mfma_f32_16x16x32_bf16 v[62:65], v[138:141], v[162:165], v[62:65]
	v_mfma_f32_16x16x32_bf16 v[62:65], v[142:145], v[166:169], v[62:65]
	v_mfma_f32_16x16x32_bf16 v[54:57], v[130:133], v[170:173], v[54:57]
	v_mfma_f32_16x16x32_bf16 v[54:57], v[134:137], v[174:177], v[54:57]
	v_mfma_f32_16x16x32_bf16 v[50:53], v[138:141], v[170:173], v[50:53]
	v_mfma_f32_16x16x32_bf16 v[50:53], v[142:145], v[174:177], v[50:53]
	v_mfma_f32_16x16x32_bf16 v[46:49], v[130:133], v[202:205], v[46:49]
	v_mfma_f32_16x16x32_bf16 v[46:49], v[134:137], v[206:209], v[46:49]
	v_mfma_f32_16x16x32_bf16 v[42:45], v[138:141], v[202:205], v[42:45]
	v_mfma_f32_16x16x32_bf16 v[42:45], v[142:145], v[206:209], v[42:45]
	v_mfma_f32_16x16x32_bf16 v[38:41], v[130:133], v[210:213], v[38:41]
	v_mfma_f32_16x16x32_bf16 v[38:41], v[134:137], v[214:217], v[38:41]
	v_mfma_f32_16x16x32_bf16 v[34:37], v[138:141], v[210:213], v[34:37]
	v_mfma_f32_16x16x32_bf16 v[34:37], v[142:145], v[214:217], v[34:37]
	v_mfma_f32_16x16x32_bf16 v[30:33], v[146:149], v[162:165], v[30:33]
	v_mfma_f32_16x16x32_bf16 v[30:33], v[150:153], v[166:169], v[30:33]
	v_mfma_f32_16x16x32_bf16 v[26:29], v[154:157], v[162:165], v[26:29]
	v_mfma_f32_16x16x32_bf16 v[26:29], v[158:161], v[166:169], v[26:29]
	v_mfma_f32_16x16x32_bf16 v[22:25], v[146:149], v[170:173], v[22:25]
	v_mfma_f32_16x16x32_bf16 v[22:25], v[150:153], v[174:177], v[22:25]
	v_mfma_f32_16x16x32_bf16 v[18:21], v[154:157], v[170:173], v[18:21]
	v_mfma_f32_16x16x32_bf16 v[18:21], v[158:161], v[174:177], v[18:21]
	v_mfma_f32_16x16x32_bf16 v[14:17], v[146:149], v[202:205], v[14:17]
	v_mfma_f32_16x16x32_bf16 v[14:17], v[150:153], v[206:209], v[14:17]
	v_mfma_f32_16x16x32_bf16 v[10:13], v[154:157], v[202:205], v[10:13]
	v_mfma_f32_16x16x32_bf16 v[10:13], v[158:161], v[206:209], v[10:13]
	v_mfma_f32_16x16x32_bf16 v[6:9], v[146:149], v[210:213], v[6:9]
	v_mfma_f32_16x16x32_bf16 v[6:9], v[150:153], v[214:217], v[6:9]
	v_mfma_f32_16x16x32_bf16 v[2:5], v[154:157], v[210:213], v[2:5]
	v_mfma_f32_16x16x32_bf16 v[2:5], v[158:161], v[214:217], v[2:5]
	s_barrier
	s_add_u32 s24, s24, 0x8000
	s_addc_u32 s25, s25, 0
	s_add_u32 s68, s68, 0x8000
	s_addc_u32 s69, s69, 0
	s_cmp_ge_u32 s70, s66
	s_mov_b32 s31, s70
	s_cbranch_scc0 .LBB0_1005
	s_and_b64 vcc, exec, s[18:19]
	s_cbranch_vccnz .LBB0_1010
	v_lshl_add_u32 v162, s65, 8, v189
	s_mov_b64 s[24:25], -1
	s_and_b64 vcc, exec, s[22:23]
	s_cbranch_vccnz .LBB0_1011

.LBB0_1088:
	ds_read_b128 v[130:133], v209
	ds_read_b128 v[134:137], v209 offset:1024
	ds_read_b128 v[138:141], v209 offset:2048
	ds_read_b128 v[142:145], v209 offset:3072
	ds_read_b128 v[146:149], v210
	ds_read_b128 v[150:153], v210 offset:1024
	ds_read_b128 v[154:157], v210 offset:2048
	ds_read_b128 v[158:161], v210 offset:3072
	s_add_u32 s38, s36, 0xfff04000
	s_addc_u32 s39, s37, -1
	s_cmp_eq_u32 s72, 60
	s_cselect_b32 s42, s35, s38
	s_cselect_b32 s43, s25, s39
	s_cselect_b32 s40, s69, s70
	s_cselect_b32 s41, s23, s71
	s_add_u32 s38, s42, 0x4000
	s_addc_u32 s39, s43, 0
	s_add_i32 m0, s47, 0xc000
	ds_read_b128 v[162:165], v211
	ds_read_b128 v[166:169], v211 offset:1024
	ds_read_b128 v[170:173], v211 offset:2048
	ds_read_b128 v[174:177], v211 offset:3072
	ds_read_b128 v[196:199], v211 offset:4096
	ds_read_b128 v[200:203], v211 offset:5120
	ds_read_b128 v[214:217], v211 offset:6144
	ds_read_b128 v[218:221], v211 offset:7168
	global_load_lds_dwordx4 v188, s[36:37]
	s_add_i32 m0, s47, 0xe000
	s_nop 0
	global_load_lds_dwordx4 v190, s[36:37]
	s_waitcnt vmcnt(8)
	s_waitcnt lgkmcnt(0)
	s_barrier
	s_waitcnt lgkmcnt(0)
	v_mfma_f32_16x16x32_bf16 v[126:129], v[130:133], v[162:165], v[126:129]
	v_mfma_f32_16x16x32_bf16 v[126:129], v[134:137], v[166:169], v[126:129]
	v_mfma_f32_16x16x32_bf16 v[122:125], v[138:141], v[162:165], v[122:125]
	v_mfma_f32_16x16x32_bf16 v[122:125], v[142:145], v[166:169], v[122:125]
	v_mfma_f32_16x16x32_bf16 v[110:113], v[130:133], v[170:173], v[110:113]
	v_mfma_f32_16x16x32_bf16 v[110:113], v[134:137], v[174:177], v[110:113]
	v_mfma_f32_16x16x32_bf16 v[106:109], v[138:141], v[170:173], v[106:109]
	v_mfma_f32_16x16x32_bf16 v[106:109], v[142:145], v[174:177], v[106:109]
	v_mfma_f32_16x16x32_bf16 v[94:97], v[130:133], v[196:199], v[94:97]
	v_mfma_f32_16x16x32_bf16 v[94:97], v[134:137], v[200:203], v[94:97]
	v_mfma_f32_16x16x32_bf16 v[90:93], v[138:141], v[196:199], v[90:93]
	v_mfma_f32_16x16x32_bf16 v[90:93], v[142:145], v[200:203], v[90:93]
	v_mfma_f32_16x16x32_bf16 v[78:81], v[130:133], v[214:217], v[78:81]
	v_mfma_f32_16x16x32_bf16 v[78:81], v[134:137], v[218:221], v[78:81]
	v_mfma_f32_16x16x32_bf16 v[74:77], v[138:141], v[214:217], v[74:77]
	v_mfma_f32_16x16x32_bf16 v[74:77], v[142:145], v[218:221], v[74:77]
	v_mfma_f32_16x16x32_bf16 v[118:121], v[146:149], v[162:165], v[118:121]
	v_mfma_f32_16x16x32_bf16 v[118:121], v[150:153], v[166:169], v[118:121]
	v_mfma_f32_16x16x32_bf16 v[114:117], v[154:157], v[162:165], v[114:117]
	v_mfma_f32_16x16x32_bf16 v[114:117], v[158:161], v[166:169], v[114:117]
	v_mfma_f32_16x16x32_bf16 v[102:105], v[146:149], v[170:173], v[102:105]
	v_mfma_f32_16x16x32_bf16 v[102:105], v[150:153], v[174:177], v[102:105]
	v_mfma_f32_16x16x32_bf16 v[98:101], v[154:157], v[170:173], v[98:101]
	v_mfma_f32_16x16x32_bf16 v[98:101], v[158:161], v[174:177], v[98:101]
	v_mfma_f32_16x16x32_bf16 v[86:89], v[146:149], v[196:199], v[86:89]
	v_mfma_f32_16x16x32_bf16 v[86:89], v[150:153], v[200:203], v[86:89]
	v_mfma_f32_16x16x32_bf16 v[82:85], v[154:157], v[196:199], v[82:85]
	v_mfma_f32_16x16x32_bf16 v[82:85], v[158:161], v[200:203], v[82:85]
	v_mfma_f32_16x16x32_bf16 v[70:73], v[146:149], v[214:217], v[70:73]
	v_mfma_f32_16x16x32_bf16 v[70:73], v[150:153], v[218:221], v[70:73]
	v_mfma_f32_16x16x32_bf16 v[66:69], v[154:157], v[214:217], v[66:69]
	v_mfma_f32_16x16x32_bf16 v[66:69], v[158:161], v[218:221], v[66:69]
	s_barrier
	s_add_i32 s73, s66, s46
	s_mov_b32 m0, s73
	ds_read_b128 v[162:165], v211 offset:16384
	ds_read_b128 v[166:169], v211 offset:17408
	ds_read_b128 v[170:173], v211 offset:18432
	ds_read_b128 v[174:177], v211 offset:19456
	ds_read_b128 v[196:199], v211 offset:20480
	ds_read_b128 v[200:203], v211 offset:21504
	ds_read_b128 v[214:217], v211 offset:22528
	ds_read_b128 v[218:221], v211 offset:23552
	global_load_lds_dwordx4 v180, s[40:41]
	s_add_i32 m0, s73, 0x2000
	s_add_u32 s74, s40, 0x100000
	s_addc_u32 s75, s41, 0
	s_add_i32 s73, s67, s46
	global_load_lds_dwordx4 v184, s[40:41]
	s_mov_b32 m0, s73
	s_nop 0
	global_load_lds_dwordx4 v180, s[74:75]
	s_add_i32 m0, s73, 0x2000
	s_nop 0
	global_load_lds_dwordx4 v184, s[74:75]
	s_mov_b32 m0, s47
	s_nop 0
	global_load_lds_dwordx4 v178, s[42:43]
	s_mov_b32 m0, s59
	s_nop 0
	global_load_lds_dwordx4 v182, s[42:43]
	s_waitcnt vmcnt(8)
	s_waitcnt lgkmcnt(0)
	s_barrier
	s_waitcnt lgkmcnt(0)
	v_mfma_f32_16x16x32_bf16 v[62:65], v[130:133], v[162:165], v[62:65]
	v_mfma_f32_16x16x32_bf16 v[62:65], v[134:137], v[166:169], v[62:65]
	v_mfma_f32_16x16x32_bf16 v[58:61], v[138:141], v[162:165], v[58:61]
	v_mfma_f32_16x16x32_bf16 v[58:61], v[142:145], v[166:169], v[58:61]
	v_mfma_f32_16x16x32_bf16 v[46:49], v[130:133], v[170:173], v[46:49]
	v_mfma_f32_16x16x32_bf16 v[46:49], v[134:137], v[174:177], v[46:49]
	v_mfma_f32_16x16x32_bf16 v[42:45], v[138:141], v[170:173], v[42:45]
	v_mfma_f32_16x16x32_bf16 v[42:45], v[142:145], v[174:177], v[42:45]
	v_mfma_f32_16x16x32_bf16 v[30:33], v[130:133], v[196:199], v[30:33]
	v_mfma_f32_16x16x32_bf16 v[30:33], v[134:137], v[200:203], v[30:33]
	v_mfma_f32_16x16x32_bf16 v[26:29], v[138:141], v[196:199], v[26:29]
	v_mfma_f32_16x16x32_bf16 v[26:29], v[142:145], v[200:203], v[26:29]
	v_mfma_f32_16x16x32_bf16 v[14:17], v[130:133], v[214:217], v[14:17]
	v_mfma_f32_16x16x32_bf16 v[14:17], v[134:137], v[218:221], v[14:17]
	v_mfma_f32_16x16x32_bf16 v[10:13], v[138:141], v[214:217], v[10:13]
	v_mfma_f32_16x16x32_bf16 v[10:13], v[142:145], v[218:221], v[10:13]
	v_mfma_f32_16x16x32_bf16 v[54:57], v[146:149], v[162:165], v[54:57]
	v_mfma_f32_16x16x32_bf16 v[54:57], v[150:153], v[166:169], v[54:57]
	v_mfma_f32_16x16x32_bf16 v[50:53], v[154:157], v[162:165], v[50:53]
	v_mfma_f32_16x16x32_bf16 v[50:53], v[158:161], v[166:169], v[50:53]
	v_mfma_f32_16x16x32_bf16 v[38:41], v[146:149], v[170:173], v[38:41]
	v_mfma_f32_16x16x32_bf16 v[38:41], v[150:153], v[174:177], v[38:41]
	v_mfma_f32_16x16x32_bf16 v[34:37], v[154:157], v[170:173], v[34:37]
	v_mfma_f32_16x16x32_bf16 v[34:37], v[158:161], v[174:177], v[34:37]
	v_mfma_f32_16x16x32_bf16 v[22:25], v[146:149], v[196:199], v[22:25]
	v_mfma_f32_16x16x32_bf16 v[22:25], v[150:153], v[200:203], v[22:25]
	v_mfma_f32_16x16x32_bf16 v[18:21], v[154:157], v[196:199], v[18:21]
	v_mfma_f32_16x16x32_bf16 v[18:21], v[158:161], v[200:203], v[18:21]
	v_mfma_f32_16x16x32_bf16 v[6:9], v[146:149], v[214:217], v[6:9]
	v_mfma_f32_16x16x32_bf16 v[6:9], v[150:153], v[218:221], v[6:9]
	v_mfma_f32_16x16x32_bf16 v[2:5], v[154:157], v[214:217], v[2:5]
	v_mfma_f32_16x16x32_bf16 v[2:5], v[158:161], v[218:221], v[2:5]
	s_barrier
	s_add_i32 s73, 0, 0x18000
	s_add_i32 s74, 0, 0x1c000
	v_add_u32_e32 v142, s73, v208
	v_add_u32_e32 v158, s74, v208
	ds_read_b128 v[130:133], v142
	ds_read_b128 v[134:137], v142 offset:1024
	ds_read_b128 v[138:141], v142 offset:2048
	ds_read_b128 v[142:145], v142 offset:3072
	ds_read_b128 v[146:149], v158
	ds_read_b128 v[150:153], v158 offset:1024
	ds_read_b128 v[154:157], v158 offset:2048
	ds_read_b128 v[158:161], v158 offset:3072
	s_add_u32 s42, s42, 0x100000
	s_addc_u32 s43, s43, 0
	s_mov_b32 m0, s60
	ds_read_b128 v[162:165], v211 offset:32768
	ds_read_b128 v[166:169], v211 offset:33792
	ds_read_b128 v[170:173], v211 offset:34816
	ds_read_b128 v[174:177], v211 offset:35840
	ds_read_b128 v[196:199], v211 offset:36864
	ds_read_b128 v[200:203], v211 offset:37888
	ds_read_b128 v[214:217], v211 offset:38912
	ds_read_b128 v[218:221], v211 offset:39936
	global_load_lds_dwordx4 v178, s[42:43]
	s_mov_b32 m0, s61
	s_nop 0
	global_load_lds_dwordx4 v182, s[42:43]
	s_waitcnt vmcnt(8)
	s_waitcnt lgkmcnt(0)
	s_barrier
	s_waitcnt lgkmcnt(0)
	v_mfma_f32_16x16x32_bf16 v[126:129], v[130:133], v[162:165], v[126:129]
	v_mfma_f32_16x16x32_bf16 v[126:129], v[134:137], v[166:169], v[126:129]
	v_mfma_f32_16x16x32_bf16 v[122:125], v[138:141], v[162:165], v[122:125]
	v_mfma_f32_16x16x32_bf16 v[122:125], v[142:145], v[166:169], v[122:125]
	v_mfma_f32_16x16x32_bf16 v[110:113], v[130:133], v[170:173], v[110:113]
	v_mfma_f32_16x16x32_bf16 v[110:113], v[134:137], v[174:177], v[110:113]
	v_mfma_f32_16x16x32_bf16 v[106:109], v[138:141], v[170:173], v[106:109]
	v_mfma_f32_16x16x32_bf16 v[106:109], v[142:145], v[174:177], v[106:109]
	v_mfma_f32_16x16x32_bf16 v[94:97], v[130:133], v[196:199], v[94:97]
	v_mfma_f32_16x16x32_bf16 v[94:97], v[134:137], v[200:203], v[94:97]
	v_mfma_f32_16x16x32_bf16 v[90:93], v[138:141], v[196:199], v[90:93]
	v_mfma_f32_16x16x32_bf16 v[90:93], v[142:145], v[200:203], v[90:93]
	v_mfma_f32_16x16x32_bf16 v[78:81], v[130:133], v[214:217], v[78:81]
	v_mfma_f32_16x16x32_bf16 v[78:81], v[134:137], v[218:221], v[78:81]
	v_mfma_f32_16x16x32_bf16 v[74:77], v[138:141], v[214:217], v[74:77]
	v_mfma_f32_16x16x32_bf16 v[74:77], v[142:145], v[218:221], v[74:77]
	v_mfma_f32_16x16x32_bf16 v[118:121], v[146:149], v[162:165], v[118:121]
	v_mfma_f32_16x16x32_bf16 v[118:121], v[150:153], v[166:169], v[118:121]
	v_mfma_f32_16x16x32_bf16 v[114:117], v[154:157], v[162:165], v[114:117]
	v_mfma_f32_16x16x32_bf16 v[114:117], v[158:161], v[166:169], v[114:117]
	v_mfma_f32_16x16x32_bf16 v[102:105], v[146:149], v[170:173], v[102:105]
	v_mfma_f32_16x16x32_bf16 v[102:105], v[150:153], v[174:177], v[102:105]
	v_mfma_f32_16x16x32_bf16 v[98:101], v[154:157], v[170:173], v[98:101]
	v_mfma_f32_16x16x32_bf16 v[98:101], v[158:161], v[174:177], v[98:101]
	v_mfma_f32_16x16x32_bf16 v[86:89], v[146:149], v[196:199], v[86:89]
	v_mfma_f32_16x16x32_bf16 v[86:89], v[150:153], v[200:203], v[86:89]
	v_mfma_f32_16x16x32_bf16 v[82:85], v[154:157], v[196:199], v[82:85]
	v_mfma_f32_16x16x32_bf16 v[82:85], v[158:161], v[200:203], v[82:85]
	v_mfma_f32_16x16x32_bf16 v[70:73], v[146:149], v[214:217], v[70:73]
	v_mfma_f32_16x16x32_bf16 v[70:73], v[150:153], v[218:221], v[70:73]
	v_mfma_f32_16x16x32_bf16 v[66:69], v[154:157], v[214:217], v[66:69]
	v_mfma_f32_16x16x32_bf16 v[66:69], v[158:161], v[218:221], v[66:69]
	s_barrier
	s_add_u32 s42, s40, 0x4000
	s_addc_u32 s43, s41, 0
	s_add_i32 s73, s73, s46
	s_mov_b32 m0, s73
	ds_read_b128 v[162:165], v211 offset:49152
	ds_read_b128 v[166:169], v211 offset:50176
	ds_read_b128 v[170:173], v211 offset:51200
	ds_read_b128 v[174:177], v211 offset:52224
	ds_read_b128 v[196:199], v211 offset:53248
	ds_read_b128 v[200:203], v211 offset:54272
	ds_read_b128 v[214:217], v211 offset:55296
	ds_read_b128 v[218:221], v211 offset:56320
	global_load_lds_dwordx4 v180, s[42:43]
	s_add_i32 m0, s73, 0x2000
	s_add_u32 s40, s40, 0x104000
	s_addc_u32 s41, s41, 0
	global_load_lds_dwordx4 v184, s[42:43]
	s_add_i32 s42, s74, s46
	s_mov_b32 m0, s42
	s_nop 0
	global_load_lds_dwordx4 v180, s[40:41]
	s_add_i32 m0, s42, 0x2000
	s_nop 0
	global_load_lds_dwordx4 v184, s[40:41]
	s_mov_b32 m0, s64
	s_nop 0
	global_load_lds_dwordx4 v178, s[38:39]
	s_mov_b32 m0, s65
	s_nop 0
	global_load_lds_dwordx4 v182, s[38:39]
	s_waitcnt vmcnt(8)
	s_waitcnt lgkmcnt(0)
	s_barrier
	s_waitcnt lgkmcnt(0)
	v_mfma_f32_16x16x32_bf16 v[62:65], v[130:133], v[162:165], v[62:65]
	v_mfma_f32_16x16x32_bf16 v[62:65], v[134:137], v[166:169], v[62:65]
	v_mfma_f32_16x16x32_bf16 v[58:61], v[138:141], v[162:165], v[58:61]
	v_mfma_f32_16x16x32_bf16 v[58:61], v[142:145], v[166:169], v[58:61]
	v_mfma_f32_16x16x32_bf16 v[46:49], v[130:133], v[170:173], v[46:49]
	v_mfma_f32_16x16x32_bf16 v[46:49], v[134:137], v[174:177], v[46:49]
	v_mfma_f32_16x16x32_bf16 v[42:45], v[138:141], v[170:173], v[42:45]
	v_mfma_f32_16x16x32_bf16 v[42:45], v[142:145], v[174:177], v[42:45]
	v_mfma_f32_16x16x32_bf16 v[30:33], v[130:133], v[196:199], v[30:33]
	v_mfma_f32_16x16x32_bf16 v[30:33], v[134:137], v[200:203], v[30:33]
	v_mfma_f32_16x16x32_bf16 v[26:29], v[138:141], v[196:199], v[26:29]
	v_mfma_f32_16x16x32_bf16 v[26:29], v[142:145], v[200:203], v[26:29]
	v_mfma_f32_16x16x32_bf16 v[14:17], v[130:133], v[214:217], v[14:17]
	v_mfma_f32_16x16x32_bf16 v[14:17], v[134:137], v[218:221], v[14:17]
	v_mfma_f32_16x16x32_bf16 v[10:13], v[138:141], v[214:217], v[10:13]
	v_mfma_f32_16x16x32_bf16 v[10:13], v[142:145], v[218:221], v[10:13]
	v_mfma_f32_16x16x32_bf16 v[54:57], v[146:149], v[162:165], v[54:57]
	v_mfma_f32_16x16x32_bf16 v[54:57], v[150:153], v[166:169], v[54:57]
	v_mfma_f32_16x16x32_bf16 v[50:53], v[154:157], v[162:165], v[50:53]
	v_mfma_f32_16x16x32_bf16 v[50:53], v[158:161], v[166:169], v[50:53]
	v_mfma_f32_16x16x32_bf16 v[38:41], v[146:149], v[170:173], v[38:41]
	v_mfma_f32_16x16x32_bf16 v[38:41], v[150:153], v[174:177], v[38:41]
	v_mfma_f32_16x16x32_bf16 v[34:37], v[154:157], v[170:173], v[34:37]
	v_mfma_f32_16x16x32_bf16 v[34:37], v[158:161], v[174:177], v[34:37]
	v_mfma_f32_16x16x32_bf16 v[22:25], v[146:149], v[196:199], v[22:25]
	v_mfma_f32_16x16x32_bf16 v[22:25], v[150:153], v[200:203], v[22:25]
	v_mfma_f32_16x16x32_bf16 v[18:21], v[154:157], v[196:199], v[18:21]
	v_mfma_f32_16x16x32_bf16 v[18:21], v[158:161], v[200:203], v[18:21]
	v_mfma_f32_16x16x32_bf16 v[6:9], v[146:149], v[214:217], v[6:9]
	v_mfma_f32_16x16x32_bf16 v[6:9], v[150:153], v[218:221], v[6:9]
	v_mfma_f32_16x16x32_bf16 v[2:5], v[154:157], v[214:217], v[2:5]
	v_mfma_f32_16x16x32_bf16 v[2:5], v[158:161], v[218:221], v[2:5]
	s_barrier
	s_add_i32 s72, s72, 2
	s_add_u32 s36, s36, 0x8000
	s_addc_u32 s37, s37, 0
	s_add_u32 s70, s70, 0x8000
	s_addc_u32 s71, s71, 0
	s_cmp_gt_u32 s72, 61
	s_cbranch_scc0 .LBB0_1088
	s_and_b64 vcc, exec, s[20:21]
	s_cbranch_vccz .LBB0_1091
	s_barrier

.LBB0_1215:
	ds_read_b128 v[160:163], v154
	ds_read_b128 v[164:167], v154 offset:1024
	ds_read_b128 v[168:171], v154 offset:2048
	ds_read_b128 v[172:175], v154 offset:3072
	ds_read_b128 v[176:179], v155
	ds_read_b128 v[180:183], v155 offset:1024
	ds_read_b128 v[184:187], v155 offset:2048
	ds_read_b128 v[188:191], v155 offset:3072
	s_add_u32 s30, s28, 0xfff04000
	s_addc_u32 s31, s29, -1
	s_cmp_eq_u32 s61, 60
	s_cselect_b32 s36, s56, s30
	s_cselect_b32 s37, s21, s31
	s_cselect_b32 s34, s57, s59
	s_cselect_b32 s35, s19, s60
	s_add_u32 s30, s36, 0x4000
	s_addc_u32 s31, s37, 0
	s_add_i32 m0, s39, 0xc000
	ds_read_b128 v[192:195], v156
	ds_read_b128 v[196:199], v156 offset:1024
	ds_read_b128 v[200:203], v156 offset:2048
	ds_read_b128 v[204:207], v156 offset:3072
	ds_read_b128 v[208:211], v156 offset:4096
	ds_read_b128 v[212:215], v156 offset:5120
	ds_read_b128 v[216:219], v156 offset:6144
	ds_read_b128 v[220:223], v156 offset:7168
	global_load_lds_dwordx4 v140, s[28:29]
	s_add_i32 m0, s39, 0xe000
	s_nop 0
	global_load_lds_dwordx4 v142, s[28:29]
	s_waitcnt vmcnt(8)
	s_waitcnt lgkmcnt(0)
	s_barrier
	s_waitcnt lgkmcnt(0)
	v_mfma_f32_16x16x32_bf16 v[126:129], v[160:163], v[192:195], v[126:129]
	v_mfma_f32_16x16x32_bf16 v[126:129], v[164:167], v[196:199], v[126:129]
	v_mfma_f32_16x16x32_bf16 v[122:125], v[168:171], v[192:195], v[122:125]
	v_mfma_f32_16x16x32_bf16 v[122:125], v[172:175], v[196:199], v[122:125]
	v_mfma_f32_16x16x32_bf16 v[110:113], v[160:163], v[200:203], v[110:113]
	v_mfma_f32_16x16x32_bf16 v[110:113], v[164:167], v[204:207], v[110:113]
	v_mfma_f32_16x16x32_bf16 v[106:109], v[168:171], v[200:203], v[106:109]
	v_mfma_f32_16x16x32_bf16 v[106:109], v[172:175], v[204:207], v[106:109]
	v_mfma_f32_16x16x32_bf16 v[94:97], v[160:163], v[208:211], v[94:97]
	v_mfma_f32_16x16x32_bf16 v[94:97], v[164:167], v[212:215], v[94:97]
	v_mfma_f32_16x16x32_bf16 v[90:93], v[168:171], v[208:211], v[90:93]
	v_mfma_f32_16x16x32_bf16 v[90:93], v[172:175], v[212:215], v[90:93]
	v_mfma_f32_16x16x32_bf16 v[78:81], v[160:163], v[216:219], v[78:81]
	v_mfma_f32_16x16x32_bf16 v[78:81], v[164:167], v[220:223], v[78:81]
	v_mfma_f32_16x16x32_bf16 v[74:77], v[168:171], v[216:219], v[74:77]
	v_mfma_f32_16x16x32_bf16 v[74:77], v[172:175], v[220:223], v[74:77]
	v_mfma_f32_16x16x32_bf16 v[118:121], v[176:179], v[192:195], v[118:121]
	v_mfma_f32_16x16x32_bf16 v[118:121], v[180:183], v[196:199], v[118:121]
	v_mfma_f32_16x16x32_bf16 v[114:117], v[184:187], v[192:195], v[114:117]
	v_mfma_f32_16x16x32_bf16 v[114:117], v[188:191], v[196:199], v[114:117]
	v_mfma_f32_16x16x32_bf16 v[102:105], v[176:179], v[200:203], v[102:105]
	v_mfma_f32_16x16x32_bf16 v[102:105], v[180:183], v[204:207], v[102:105]
	v_mfma_f32_16x16x32_bf16 v[98:101], v[184:187], v[200:203], v[98:101]
	v_mfma_f32_16x16x32_bf16 v[98:101], v[188:191], v[204:207], v[98:101]
	v_mfma_f32_16x16x32_bf16 v[86:89], v[176:179], v[208:211], v[86:89]
	v_mfma_f32_16x16x32_bf16 v[86:89], v[180:183], v[212:215], v[86:89]
	v_mfma_f32_16x16x32_bf16 v[82:85], v[184:187], v[208:211], v[82:85]
	v_mfma_f32_16x16x32_bf16 v[82:85], v[188:191], v[212:215], v[82:85]
	v_mfma_f32_16x16x32_bf16 v[70:73], v[176:179], v[216:219], v[70:73]
	v_mfma_f32_16x16x32_bf16 v[70:73], v[180:183], v[220:223], v[70:73]
	v_mfma_f32_16x16x32_bf16 v[66:69], v[184:187], v[216:219], v[66:69]
	v_mfma_f32_16x16x32_bf16 v[66:69], v[188:191], v[220:223], v[66:69]
	s_barrier
	s_add_i32 s62, s47, s38
	s_mov_b32 m0, s62
	ds_read_b128 v[192:195], v156 offset:16384
	ds_read_b128 v[196:199], v156 offset:17408
	ds_read_b128 v[200:203], v156 offset:18432
	ds_read_b128 v[204:207], v156 offset:19456
	ds_read_b128 v[208:211], v156 offset:20480
	ds_read_b128 v[212:215], v156 offset:21504
	ds_read_b128 v[216:219], v156 offset:22528
	ds_read_b128 v[220:223], v156 offset:23552
	global_load_lds_dwordx4 v134, s[34:35]
	s_add_i32 m0, s62, 0x2000
	s_add_u32 s62, s34, 0x100000
	s_addc_u32 s63, s35, 0
	s_add_i32 s64, s54, s38
	global_load_lds_dwordx4 v130, s[34:35]
	s_mov_b32 m0, s64
	s_nop 0
	global_load_lds_dwordx4 v134, s[62:63]
	s_add_i32 m0, s64, 0x2000
	s_nop 0
	global_load_lds_dwordx4 v130, s[62:63]
	s_mov_b32 m0, s39
	s_nop 0
	global_load_lds_dwordx4 v136, s[36:37]
	s_mov_b32 m0, s40
	s_nop 0
	global_load_lds_dwordx4 v132, s[36:37]
	s_waitcnt vmcnt(8)
	s_waitcnt lgkmcnt(0)
	s_barrier
	s_waitcnt lgkmcnt(0)
	v_mfma_f32_16x16x32_bf16 v[62:65], v[160:163], v[192:195], v[62:65]
	v_mfma_f32_16x16x32_bf16 v[62:65], v[164:167], v[196:199], v[62:65]
	v_mfma_f32_16x16x32_bf16 v[58:61], v[168:171], v[192:195], v[58:61]
	v_mfma_f32_16x16x32_bf16 v[58:61], v[172:175], v[196:199], v[58:61]
	v_mfma_f32_16x16x32_bf16 v[46:49], v[160:163], v[200:203], v[46:49]
	v_mfma_f32_16x16x32_bf16 v[46:49], v[164:167], v[204:207], v[46:49]
	v_mfma_f32_16x16x32_bf16 v[42:45], v[168:171], v[200:203], v[42:45]
	v_mfma_f32_16x16x32_bf16 v[42:45], v[172:175], v[204:207], v[42:45]
	v_mfma_f32_16x16x32_bf16 v[30:33], v[160:163], v[208:211], v[30:33]
	v_mfma_f32_16x16x32_bf16 v[30:33], v[164:167], v[212:215], v[30:33]
	v_mfma_f32_16x16x32_bf16 v[26:29], v[168:171], v[208:211], v[26:29]
	v_mfma_f32_16x16x32_bf16 v[26:29], v[172:175], v[212:215], v[26:29]
	v_mfma_f32_16x16x32_bf16 v[14:17], v[160:163], v[216:219], v[14:17]
	v_mfma_f32_16x16x32_bf16 v[14:17], v[164:167], v[220:223], v[14:17]
	v_mfma_f32_16x16x32_bf16 v[10:13], v[168:171], v[216:219], v[10:13]
	v_mfma_f32_16x16x32_bf16 v[10:13], v[172:175], v[220:223], v[10:13]
	v_mfma_f32_16x16x32_bf16 v[54:57], v[176:179], v[192:195], v[54:57]
	v_mfma_f32_16x16x32_bf16 v[54:57], v[180:183], v[196:199], v[54:57]
	v_mfma_f32_16x16x32_bf16 v[50:53], v[184:187], v[192:195], v[50:53]
	v_mfma_f32_16x16x32_bf16 v[50:53], v[188:191], v[196:199], v[50:53]
	v_mfma_f32_16x16x32_bf16 v[38:41], v[176:179], v[200:203], v[38:41]
	v_mfma_f32_16x16x32_bf16 v[38:41], v[180:183], v[204:207], v[38:41]
	v_mfma_f32_16x16x32_bf16 v[34:37], v[184:187], v[200:203], v[34:37]
	v_mfma_f32_16x16x32_bf16 v[34:37], v[188:191], v[204:207], v[34:37]
	v_mfma_f32_16x16x32_bf16 v[22:25], v[176:179], v[208:211], v[22:25]
	v_mfma_f32_16x16x32_bf16 v[22:25], v[180:183], v[212:215], v[22:25]
	v_mfma_f32_16x16x32_bf16 v[18:21], v[184:187], v[208:211], v[18:21]
	v_mfma_f32_16x16x32_bf16 v[18:21], v[188:191], v[212:215], v[18:21]
	v_mfma_f32_16x16x32_bf16 v[6:9], v[176:179], v[216:219], v[6:9]
	v_mfma_f32_16x16x32_bf16 v[6:9], v[180:183], v[220:223], v[6:9]
	v_mfma_f32_16x16x32_bf16 v[2:5], v[184:187], v[216:219], v[2:5]
	v_mfma_f32_16x16x32_bf16 v[2:5], v[188:191], v[220:223], v[2:5]
	s_barrier
	s_add_i32 s62, 0, 0x18000
	v_add_u32_e32 v138, s62, v153
	s_add_i32 s63, 0, 0x1c000
	ds_read_b128 v[160:163], v138
	ds_read_b128 v[164:167], v138 offset:1024
	ds_read_b128 v[168:171], v138 offset:2048
	ds_read_b128 v[172:175], v138 offset:3072
	v_add_u32_e32 v138, s63, v153
	ds_read_b128 v[176:179], v138
	ds_read_b128 v[180:183], v138 offset:1024
	ds_read_b128 v[184:187], v138 offset:2048
	ds_read_b128 v[188:191], v138 offset:3072
	s_add_u32 s36, s36, 0x100000
	s_addc_u32 s37, s37, 0
	s_mov_b32 m0, s41
	ds_read_b128 v[192:195], v156 offset:32768
	ds_read_b128 v[196:199], v156 offset:33792
	ds_read_b128 v[200:203], v156 offset:34816
	ds_read_b128 v[204:207], v156 offset:35840
	ds_read_b128 v[208:211], v156 offset:36864
	ds_read_b128 v[212:215], v156 offset:37888
	ds_read_b128 v[216:219], v156 offset:38912
	ds_read_b128 v[220:223], v156 offset:39936
	global_load_lds_dwordx4 v136, s[36:37]
	s_mov_b32 m0, s42
	s_nop 0
	global_load_lds_dwordx4 v132, s[36:37]
	s_waitcnt vmcnt(8)
	s_waitcnt lgkmcnt(0)
	s_barrier
	s_waitcnt lgkmcnt(0)
	v_mfma_f32_16x16x32_bf16 v[126:129], v[160:163], v[192:195], v[126:129]
	v_mfma_f32_16x16x32_bf16 v[126:129], v[164:167], v[196:199], v[126:129]
	v_mfma_f32_16x16x32_bf16 v[122:125], v[168:171], v[192:195], v[122:125]
	v_mfma_f32_16x16x32_bf16 v[122:125], v[172:175], v[196:199], v[122:125]
	v_mfma_f32_16x16x32_bf16 v[110:113], v[160:163], v[200:203], v[110:113]
	v_mfma_f32_16x16x32_bf16 v[110:113], v[164:167], v[204:207], v[110:113]
	v_mfma_f32_16x16x32_bf16 v[106:109], v[168:171], v[200:203], v[106:109]
	v_mfma_f32_16x16x32_bf16 v[106:109], v[172:175], v[204:207], v[106:109]
	v_mfma_f32_16x16x32_bf16 v[94:97], v[160:163], v[208:211], v[94:97]
	v_mfma_f32_16x16x32_bf16 v[94:97], v[164:167], v[212:215], v[94:97]
	v_mfma_f32_16x16x32_bf16 v[90:93], v[168:171], v[208:211], v[90:93]
	v_mfma_f32_16x16x32_bf16 v[90:93], v[172:175], v[212:215], v[90:93]
	v_mfma_f32_16x16x32_bf16 v[78:81], v[160:163], v[216:219], v[78:81]
	v_mfma_f32_16x16x32_bf16 v[78:81], v[164:167], v[220:223], v[78:81]
	v_mfma_f32_16x16x32_bf16 v[74:77], v[168:171], v[216:219], v[74:77]
	v_mfma_f32_16x16x32_bf16 v[74:77], v[172:175], v[220:223], v[74:77]
	v_mfma_f32_16x16x32_bf16 v[118:121], v[176:179], v[192:195], v[118:121]
	v_mfma_f32_16x16x32_bf16 v[118:121], v[180:183], v[196:199], v[118:121]
	v_mfma_f32_16x16x32_bf16 v[114:117], v[184:187], v[192:195], v[114:117]
	v_mfma_f32_16x16x32_bf16 v[114:117], v[188:191], v[196:199], v[114:117]
	v_mfma_f32_16x16x32_bf16 v[102:105], v[176:179], v[200:203], v[102:105]
	v_mfma_f32_16x16x32_bf16 v[102:105], v[180:183], v[204:207], v[102:105]
	v_mfma_f32_16x16x32_bf16 v[98:101], v[184:187], v[200:203], v[98:101]
	v_mfma_f32_16x16x32_bf16 v[98:101], v[188:191], v[204:207], v[98:101]
	v_mfma_f32_16x16x32_bf16 v[86:89], v[176:179], v[208:211], v[86:89]
	v_mfma_f32_16x16x32_bf16 v[86:89], v[180:183], v[212:215], v[86:89]
	v_mfma_f32_16x16x32_bf16 v[82:85], v[184:187], v[208:211], v[82:85]
	v_mfma_f32_16x16x32_bf16 v[82:85], v[188:191], v[212:215], v[82:85]
	v_mfma_f32_16x16x32_bf16 v[70:73], v[176:179], v[216:219], v[70:73]
	v_mfma_f32_16x16x32_bf16 v[70:73], v[180:183], v[220:223], v[70:73]
	v_mfma_f32_16x16x32_bf16 v[66:69], v[184:187], v[216:219], v[66:69]
	v_mfma_f32_16x16x32_bf16 v[66:69], v[188:191], v[220:223], v[66:69]
	s_barrier
	s_add_u32 s36, s34, 0x4000
	s_addc_u32 s37, s35, 0
	s_add_i32 s62, s62, s38
	s_mov_b32 m0, s62
	ds_read_b128 v[192:195], v156 offset:49152
	ds_read_b128 v[196:199], v156 offset:50176
	ds_read_b128 v[200:203], v156 offset:51200
	ds_read_b128 v[204:207], v156 offset:52224
	ds_read_b128 v[208:211], v156 offset:53248
	ds_read_b128 v[212:215], v156 offset:54272
	ds_read_b128 v[216:219], v156 offset:55296
	ds_read_b128 v[220:223], v156 offset:56320
	global_load_lds_dwordx4 v134, s[36:37]
	s_add_i32 m0, s62, 0x2000
	s_add_u32 s34, s34, 0x104000
	s_addc_u32 s35, s35, 0
	global_load_lds_dwordx4 v130, s[36:37]
	s_add_i32 s36, s63, s38
	s_mov_b32 m0, s36
	s_nop 0
	global_load_lds_dwordx4 v134, s[34:35]
	s_add_i32 m0, s36, 0x2000
	s_nop 0
	global_load_lds_dwordx4 v130, s[34:35]
	s_mov_b32 m0, s45
	s_nop 0
	global_load_lds_dwordx4 v136, s[30:31]
	s_mov_b32 m0, s46
	s_nop 0
	global_load_lds_dwordx4 v132, s[30:31]
	s_waitcnt vmcnt(8)
	s_waitcnt lgkmcnt(0)
	s_barrier
	s_waitcnt lgkmcnt(0)
	v_mfma_f32_16x16x32_bf16 v[62:65], v[160:163], v[192:195], v[62:65]
	v_mfma_f32_16x16x32_bf16 v[62:65], v[164:167], v[196:199], v[62:65]
	v_mfma_f32_16x16x32_bf16 v[58:61], v[168:171], v[192:195], v[58:61]
	v_mfma_f32_16x16x32_bf16 v[58:61], v[172:175], v[196:199], v[58:61]
	v_mfma_f32_16x16x32_bf16 v[46:49], v[160:163], v[200:203], v[46:49]
	v_mfma_f32_16x16x32_bf16 v[46:49], v[164:167], v[204:207], v[46:49]
	v_mfma_f32_16x16x32_bf16 v[42:45], v[168:171], v[200:203], v[42:45]
	v_mfma_f32_16x16x32_bf16 v[42:45], v[172:175], v[204:207], v[42:45]
	v_mfma_f32_16x16x32_bf16 v[30:33], v[160:163], v[208:211], v[30:33]
	v_mfma_f32_16x16x32_bf16 v[30:33], v[164:167], v[212:215], v[30:33]
	v_mfma_f32_16x16x32_bf16 v[26:29], v[168:171], v[208:211], v[26:29]
	v_mfma_f32_16x16x32_bf16 v[26:29], v[172:175], v[212:215], v[26:29]
	v_mfma_f32_16x16x32_bf16 v[14:17], v[160:163], v[216:219], v[14:17]
	v_mfma_f32_16x16x32_bf16 v[14:17], v[164:167], v[220:223], v[14:17]
	v_mfma_f32_16x16x32_bf16 v[10:13], v[168:171], v[216:219], v[10:13]
	v_mfma_f32_16x16x32_bf16 v[10:13], v[172:175], v[220:223], v[10:13]
	v_mfma_f32_16x16x32_bf16 v[54:57], v[176:179], v[192:195], v[54:57]
	v_mfma_f32_16x16x32_bf16 v[54:57], v[180:183], v[196:199], v[54:57]
	v_mfma_f32_16x16x32_bf16 v[50:53], v[184:187], v[192:195], v[50:53]
	v_mfma_f32_16x16x32_bf16 v[50:53], v[188:191], v[196:199], v[50:53]
	v_mfma_f32_16x16x32_bf16 v[38:41], v[176:179], v[200:203], v[38:41]
	v_mfma_f32_16x16x32_bf16 v[38:41], v[180:183], v[204:207], v[38:41]
	v_mfma_f32_16x16x32_bf16 v[34:37], v[184:187], v[200:203], v[34:37]
	v_mfma_f32_16x16x32_bf16 v[34:37], v[188:191], v[204:207], v[34:37]
	v_mfma_f32_16x16x32_bf16 v[22:25], v[176:179], v[208:211], v[22:25]
	v_mfma_f32_16x16x32_bf16 v[22:25], v[180:183], v[212:215], v[22:25]
	v_mfma_f32_16x16x32_bf16 v[18:21], v[184:187], v[208:211], v[18:21]
	v_mfma_f32_16x16x32_bf16 v[18:21], v[188:191], v[212:215], v[18:21]
	v_mfma_f32_16x16x32_bf16 v[6:9], v[176:179], v[216:219], v[6:9]
	v_mfma_f32_16x16x32_bf16 v[6:9], v[180:183], v[220:223], v[6:9]
	v_mfma_f32_16x16x32_bf16 v[2:5], v[184:187], v[216:219], v[2:5]
	v_mfma_f32_16x16x32_bf16 v[2:5], v[188:191], v[220:223], v[2:5]
	s_barrier
	s_add_i32 s61, s61, 2
	s_add_u32 s28, s28, 0x8000
	s_addc_u32 s29, s29, 0
	s_add_u32 s59, s59, 0x8000
	s_addc_u32 s60, s60, 0
	s_cmp_gt_u32 s61, 61
	s_cbranch_scc0 .LBB0_1215
	s_and_b64 vcc, exec, s[16:17]
	s_cbranch_vccz .LBB0_1218
	s_barrier

.LBB0_1292:
	ds_read_b128 v[130:133], v206
	ds_read_b128 v[134:137], v206 offset:1024
	ds_read_b128 v[138:141], v206 offset:2048
	ds_read_b128 v[142:145], v206 offset:3072
	ds_read_b128 v[146:149], v207
	ds_read_b128 v[150:153], v207 offset:1024
	ds_read_b128 v[176:179], v207 offset:2048
	ds_read_b128 v[180:183], v207 offset:3072
	s_add_u32 s42, s40, 0xffc04000
	s_addc_u32 s43, s41, -1
	s_cmpk_eq_i32 s66, 0xfc
	s_cselect_b32 s46, s29, s42
	s_cselect_b32 s47, s14, s43
	s_cselect_b32 s44, s37, s39
	s_cselect_b32 s45, s27, s65
	s_add_u32 s42, s46, 0x4000
	s_addc_u32 s43, s47, 0
	s_add_i32 m0, s53, 0xc000
	ds_read_b128 v[184:187], v208
	ds_read_b128 v[188:191], v208 offset:1024
	ds_read_b128 v[192:195], v208 offset:2048
	ds_read_b128 v[196:199], v208 offset:3072
	ds_read_b128 v[210:213], v208 offset:4096
	ds_read_b128 v[214:217], v208 offset:5120
	ds_read_b128 v[218:221], v208 offset:6144
	ds_read_b128 v[222:225], v208 offset:7168
	global_load_lds_dwordx4 v166, s[40:41]
	s_add_i32 m0, s53, 0xe000
	s_nop 0
	global_load_lds_dwordx4 v168, s[40:41]
	s_waitcnt vmcnt(8)
	s_waitcnt lgkmcnt(0)
	s_barrier
	s_waitcnt lgkmcnt(0)
	v_mfma_f32_16x16x32_bf16 v[126:129], v[130:133], v[184:187], v[126:129]
	v_mfma_f32_16x16x32_bf16 v[126:129], v[134:137], v[188:191], v[126:129]
	v_mfma_f32_16x16x32_bf16 v[122:125], v[138:141], v[184:187], v[122:125]
	v_mfma_f32_16x16x32_bf16 v[122:125], v[142:145], v[188:191], v[122:125]
	v_mfma_f32_16x16x32_bf16 v[110:113], v[130:133], v[192:195], v[110:113]
	v_mfma_f32_16x16x32_bf16 v[110:113], v[134:137], v[196:199], v[110:113]
	v_mfma_f32_16x16x32_bf16 v[106:109], v[138:141], v[192:195], v[106:109]
	v_mfma_f32_16x16x32_bf16 v[106:109], v[142:145], v[196:199], v[106:109]
	v_mfma_f32_16x16x32_bf16 v[94:97], v[130:133], v[210:213], v[94:97]
	v_mfma_f32_16x16x32_bf16 v[94:97], v[134:137], v[214:217], v[94:97]
	v_mfma_f32_16x16x32_bf16 v[90:93], v[138:141], v[210:213], v[90:93]
	v_mfma_f32_16x16x32_bf16 v[90:93], v[142:145], v[214:217], v[90:93]
	v_mfma_f32_16x16x32_bf16 v[78:81], v[130:133], v[218:221], v[78:81]
	v_mfma_f32_16x16x32_bf16 v[78:81], v[134:137], v[222:225], v[78:81]
	v_mfma_f32_16x16x32_bf16 v[74:77], v[138:141], v[218:221], v[74:77]
	v_mfma_f32_16x16x32_bf16 v[74:77], v[142:145], v[222:225], v[74:77]
	v_mfma_f32_16x16x32_bf16 v[118:121], v[146:149], v[184:187], v[118:121]
	v_mfma_f32_16x16x32_bf16 v[118:121], v[150:153], v[188:191], v[118:121]
	v_mfma_f32_16x16x32_bf16 v[114:117], v[176:179], v[184:187], v[114:117]
	v_mfma_f32_16x16x32_bf16 v[114:117], v[180:183], v[188:191], v[114:117]
	v_mfma_f32_16x16x32_bf16 v[102:105], v[146:149], v[192:195], v[102:105]
	v_mfma_f32_16x16x32_bf16 v[102:105], v[150:153], v[196:199], v[102:105]
	v_mfma_f32_16x16x32_bf16 v[98:101], v[176:179], v[192:195], v[98:101]
	v_mfma_f32_16x16x32_bf16 v[98:101], v[180:183], v[196:199], v[98:101]
	v_mfma_f32_16x16x32_bf16 v[86:89], v[146:149], v[210:213], v[86:89]
	v_mfma_f32_16x16x32_bf16 v[86:89], v[150:153], v[214:217], v[86:89]
	v_mfma_f32_16x16x32_bf16 v[82:85], v[176:179], v[210:213], v[82:85]
	v_mfma_f32_16x16x32_bf16 v[82:85], v[180:183], v[214:217], v[82:85]
	v_mfma_f32_16x16x32_bf16 v[70:73], v[146:149], v[218:221], v[70:73]
	v_mfma_f32_16x16x32_bf16 v[70:73], v[150:153], v[222:225], v[70:73]
	v_mfma_f32_16x16x32_bf16 v[66:69], v[176:179], v[218:221], v[66:69]
	v_mfma_f32_16x16x32_bf16 v[66:69], v[180:183], v[222:225], v[66:69]
	s_barrier
	s_add_i32 s67, s62, s52
	s_mov_b32 m0, s67
	ds_read_b128 v[184:187], v208 offset:16384
	ds_read_b128 v[188:191], v208 offset:17408
	ds_read_b128 v[192:195], v208 offset:18432
	ds_read_b128 v[196:199], v208 offset:19456
	ds_read_b128 v[210:213], v208 offset:20480
	ds_read_b128 v[214:217], v208 offset:21504
	ds_read_b128 v[218:221], v208 offset:22528
	ds_read_b128 v[222:225], v208 offset:23552
	global_load_lds_dwordx4 v156, s[44:45]
	s_add_i32 m0, s67, 0x2000
	s_add_u32 s68, s44, 0x400000
	s_addc_u32 s69, s45, 0
	s_add_i32 s67, s63, s52
	global_load_lds_dwordx4 v160, s[44:45]
	s_mov_b32 m0, s67
	s_nop 0
	global_load_lds_dwordx4 v156, s[68:69]
	s_add_i32 m0, s67, 0x2000
	s_nop 0
	global_load_lds_dwordx4 v160, s[68:69]
	s_mov_b32 m0, s53
	s_nop 0
	global_load_lds_dwordx4 v154, s[46:47]
	s_mov_b32 m0, s54
	s_nop 0
	global_load_lds_dwordx4 v158, s[46:47]
	s_waitcnt vmcnt(8)
	s_waitcnt lgkmcnt(0)
	s_barrier
	s_waitcnt lgkmcnt(0)
	v_mfma_f32_16x16x32_bf16 v[62:65], v[130:133], v[184:187], v[62:65]
	v_mfma_f32_16x16x32_bf16 v[62:65], v[134:137], v[188:191], v[62:65]
	v_mfma_f32_16x16x32_bf16 v[58:61], v[138:141], v[184:187], v[58:61]
	v_mfma_f32_16x16x32_bf16 v[58:61], v[142:145], v[188:191], v[58:61]
	v_mfma_f32_16x16x32_bf16 v[46:49], v[130:133], v[192:195], v[46:49]
	v_mfma_f32_16x16x32_bf16 v[46:49], v[134:137], v[196:199], v[46:49]
	v_mfma_f32_16x16x32_bf16 v[42:45], v[138:141], v[192:195], v[42:45]
	v_mfma_f32_16x16x32_bf16 v[42:45], v[142:145], v[196:199], v[42:45]
	v_mfma_f32_16x16x32_bf16 v[30:33], v[130:133], v[210:213], v[30:33]
	v_mfma_f32_16x16x32_bf16 v[30:33], v[134:137], v[214:217], v[30:33]
	v_mfma_f32_16x16x32_bf16 v[26:29], v[138:141], v[210:213], v[26:29]
	v_mfma_f32_16x16x32_bf16 v[26:29], v[142:145], v[214:217], v[26:29]
	v_mfma_f32_16x16x32_bf16 v[14:17], v[130:133], v[218:221], v[14:17]
	v_mfma_f32_16x16x32_bf16 v[14:17], v[134:137], v[222:225], v[14:17]
	v_mfma_f32_16x16x32_bf16 v[10:13], v[138:141], v[218:221], v[10:13]
	v_mfma_f32_16x16x32_bf16 v[10:13], v[142:145], v[222:225], v[10:13]
	v_mfma_f32_16x16x32_bf16 v[54:57], v[146:149], v[184:187], v[54:57]
	v_mfma_f32_16x16x32_bf16 v[54:57], v[150:153], v[188:191], v[54:57]
	v_mfma_f32_16x16x32_bf16 v[50:53], v[176:179], v[184:187], v[50:53]
	v_mfma_f32_16x16x32_bf16 v[50:53], v[180:183], v[188:191], v[50:53]
	v_mfma_f32_16x16x32_bf16 v[38:41], v[146:149], v[192:195], v[38:41]
	v_mfma_f32_16x16x32_bf16 v[38:41], v[150:153], v[196:199], v[38:41]
	v_mfma_f32_16x16x32_bf16 v[34:37], v[176:179], v[192:195], v[34:37]
	v_mfma_f32_16x16x32_bf16 v[34:37], v[180:183], v[196:199], v[34:37]
	v_mfma_f32_16x16x32_bf16 v[22:25], v[146:149], v[210:213], v[22:25]
	v_mfma_f32_16x16x32_bf16 v[22:25], v[150:153], v[214:217], v[22:25]
	v_mfma_f32_16x16x32_bf16 v[18:21], v[176:179], v[210:213], v[18:21]
	v_mfma_f32_16x16x32_bf16 v[18:21], v[180:183], v[214:217], v[18:21]
	v_mfma_f32_16x16x32_bf16 v[6:9], v[146:149], v[218:221], v[6:9]
	v_mfma_f32_16x16x32_bf16 v[6:9], v[150:153], v[222:225], v[6:9]
	v_mfma_f32_16x16x32_bf16 v[2:5], v[176:179], v[218:221], v[2:5]
	v_mfma_f32_16x16x32_bf16 v[2:5], v[180:183], v[222:225], v[2:5]
	s_barrier
	s_add_i32 s67, 0, 0x18000
	s_add_i32 s68, 0, 0x1c000
	v_add_u32_e32 v142, s67, v203
	v_add_u32_e32 v162, s68, v203
	ds_read_b128 v[130:133], v142
	ds_read_b128 v[134:137], v142 offset:1024
	ds_read_b128 v[138:141], v142 offset:2048
	ds_read_b128 v[142:145], v142 offset:3072
	ds_read_b128 v[146:149], v162
	ds_read_b128 v[150:153], v162 offset:1024
	ds_read_b128 v[176:179], v162 offset:2048
	ds_read_b128 v[180:183], v162 offset:3072
	s_add_u32 s46, s46, 0x400000
	s_addc_u32 s47, s47, 0
	s_mov_b32 m0, s55
	ds_read_b128 v[184:187], v208 offset:32768
	ds_read_b128 v[188:191], v208 offset:33792
	ds_read_b128 v[192:195], v208 offset:34816
	ds_read_b128 v[196:199], v208 offset:35840
	ds_read_b128 v[210:213], v208 offset:36864
	ds_read_b128 v[214:217], v208 offset:37888
	ds_read_b128 v[218:221], v208 offset:38912
	ds_read_b128 v[222:225], v208 offset:39936
	global_load_lds_dwordx4 v154, s[46:47]
	s_mov_b32 m0, s56
	s_nop 0
	global_load_lds_dwordx4 v158, s[46:47]
	s_waitcnt vmcnt(8)
	s_waitcnt lgkmcnt(0)
	s_barrier
	s_waitcnt lgkmcnt(0)
	v_mfma_f32_16x16x32_bf16 v[126:129], v[130:133], v[184:187], v[126:129]
	v_mfma_f32_16x16x32_bf16 v[126:129], v[134:137], v[188:191], v[126:129]
	v_mfma_f32_16x16x32_bf16 v[122:125], v[138:141], v[184:187], v[122:125]
	v_mfma_f32_16x16x32_bf16 v[122:125], v[142:145], v[188:191], v[122:125]
	v_mfma_f32_16x16x32_bf16 v[110:113], v[130:133], v[192:195], v[110:113]
	v_mfma_f32_16x16x32_bf16 v[110:113], v[134:137], v[196:199], v[110:113]
	v_mfma_f32_16x16x32_bf16 v[106:109], v[138:141], v[192:195], v[106:109]
	v_mfma_f32_16x16x32_bf16 v[106:109], v[142:145], v[196:199], v[106:109]
	v_mfma_f32_16x16x32_bf16 v[94:97], v[130:133], v[210:213], v[94:97]
	v_mfma_f32_16x16x32_bf16 v[94:97], v[134:137], v[214:217], v[94:97]
	v_mfma_f32_16x16x32_bf16 v[90:93], v[138:141], v[210:213], v[90:93]
	v_mfma_f32_16x16x32_bf16 v[90:93], v[142:145], v[214:217], v[90:93]
	v_mfma_f32_16x16x32_bf16 v[78:81], v[130:133], v[218:221], v[78:81]
	v_mfma_f32_16x16x32_bf16 v[78:81], v[134:137], v[222:225], v[78:81]
	v_mfma_f32_16x16x32_bf16 v[74:77], v[138:141], v[218:221], v[74:77]
	v_mfma_f32_16x16x32_bf16 v[74:77], v[142:145], v[222:225], v[74:77]
	v_mfma_f32_16x16x32_bf16 v[118:121], v[146:149], v[184:187], v[118:121]
	v_mfma_f32_16x16x32_bf16 v[118:121], v[150:153], v[188:191], v[118:121]
	v_mfma_f32_16x16x32_bf16 v[114:117], v[176:179], v[184:187], v[114:117]
	v_mfma_f32_16x16x32_bf16 v[114:117], v[180:183], v[188:191], v[114:117]
	v_mfma_f32_16x16x32_bf16 v[102:105], v[146:149], v[192:195], v[102:105]
	v_mfma_f32_16x16x32_bf16 v[102:105], v[150:153], v[196:199], v[102:105]
	v_mfma_f32_16x16x32_bf16 v[98:101], v[176:179], v[192:195], v[98:101]
	v_mfma_f32_16x16x32_bf16 v[98:101], v[180:183], v[196:199], v[98:101]
	v_mfma_f32_16x16x32_bf16 v[86:89], v[146:149], v[210:213], v[86:89]
	v_mfma_f32_16x16x32_bf16 v[86:89], v[150:153], v[214:217], v[86:89]
	v_mfma_f32_16x16x32_bf16 v[82:85], v[176:179], v[210:213], v[82:85]
	v_mfma_f32_16x16x32_bf16 v[82:85], v[180:183], v[214:217], v[82:85]
	v_mfma_f32_16x16x32_bf16 v[70:73], v[146:149], v[218:221], v[70:73]
	v_mfma_f32_16x16x32_bf16 v[70:73], v[150:153], v[222:225], v[70:73]
	v_mfma_f32_16x16x32_bf16 v[66:69], v[176:179], v[218:221], v[66:69]
	v_mfma_f32_16x16x32_bf16 v[66:69], v[180:183], v[222:225], v[66:69]
	s_barrier
	s_add_u32 s46, s44, 0x4000
	s_addc_u32 s47, s45, 0
	s_add_i32 s67, s67, s52
	s_mov_b32 m0, s67
	ds_read_b128 v[184:187], v208 offset:49152
	ds_read_b128 v[188:191], v208 offset:50176
	ds_read_b128 v[192:195], v208 offset:51200
	ds_read_b128 v[196:199], v208 offset:52224
	ds_read_b128 v[210:213], v208 offset:53248
	ds_read_b128 v[214:217], v208 offset:54272
	ds_read_b128 v[218:221], v208 offset:55296
	ds_read_b128 v[222:225], v208 offset:56320
	global_load_lds_dwordx4 v156, s[46:47]
	s_add_i32 m0, s67, 0x2000
	s_add_u32 s44, s44, 0x404000
	s_addc_u32 s45, s45, 0
	global_load_lds_dwordx4 v160, s[46:47]
	s_add_i32 s46, s68, s52
	s_mov_b32 m0, s46
	s_nop 0
	global_load_lds_dwordx4 v156, s[44:45]
	s_add_i32 m0, s46, 0x2000
	s_nop 0
	global_load_lds_dwordx4 v160, s[44:45]
	s_mov_b32 m0, s60
	s_nop 0
	global_load_lds_dwordx4 v154, s[42:43]
	s_mov_b32 m0, s61
	s_nop 0
	global_load_lds_dwordx4 v158, s[42:43]
	s_waitcnt vmcnt(8)
	s_waitcnt lgkmcnt(0)
	s_barrier
	s_waitcnt lgkmcnt(0)
	v_mfma_f32_16x16x32_bf16 v[62:65], v[130:133], v[184:187], v[62:65]
	v_mfma_f32_16x16x32_bf16 v[62:65], v[134:137], v[188:191], v[62:65]
	v_mfma_f32_16x16x32_bf16 v[58:61], v[138:141], v[184:187], v[58:61]
	v_mfma_f32_16x16x32_bf16 v[58:61], v[142:145], v[188:191], v[58:61]
	v_mfma_f32_16x16x32_bf16 v[46:49], v[130:133], v[192:195], v[46:49]
	v_mfma_f32_16x16x32_bf16 v[46:49], v[134:137], v[196:199], v[46:49]
	v_mfma_f32_16x16x32_bf16 v[42:45], v[138:141], v[192:195], v[42:45]
	v_mfma_f32_16x16x32_bf16 v[42:45], v[142:145], v[196:199], v[42:45]
	v_mfma_f32_16x16x32_bf16 v[30:33], v[130:133], v[210:213], v[30:33]
	v_mfma_f32_16x16x32_bf16 v[30:33], v[134:137], v[214:217], v[30:33]
	v_mfma_f32_16x16x32_bf16 v[26:29], v[138:141], v[210:213], v[26:29]
	v_mfma_f32_16x16x32_bf16 v[26:29], v[142:145], v[214:217], v[26:29]
	v_mfma_f32_16x16x32_bf16 v[14:17], v[130:133], v[218:221], v[14:17]
	v_mfma_f32_16x16x32_bf16 v[14:17], v[134:137], v[222:225], v[14:17]
	v_mfma_f32_16x16x32_bf16 v[10:13], v[138:141], v[218:221], v[10:13]
	v_mfma_f32_16x16x32_bf16 v[10:13], v[142:145], v[222:225], v[10:13]
	v_mfma_f32_16x16x32_bf16 v[54:57], v[146:149], v[184:187], v[54:57]
	v_mfma_f32_16x16x32_bf16 v[54:57], v[150:153], v[188:191], v[54:57]
	v_mfma_f32_16x16x32_bf16 v[50:53], v[176:179], v[184:187], v[50:53]
	v_mfma_f32_16x16x32_bf16 v[50:53], v[180:183], v[188:191], v[50:53]
	v_mfma_f32_16x16x32_bf16 v[38:41], v[146:149], v[192:195], v[38:41]
	v_mfma_f32_16x16x32_bf16 v[38:41], v[150:153], v[196:199], v[38:41]
	v_mfma_f32_16x16x32_bf16 v[34:37], v[176:179], v[192:195], v[34:37]
	v_mfma_f32_16x16x32_bf16 v[34:37], v[180:183], v[196:199], v[34:37]
	v_mfma_f32_16x16x32_bf16 v[22:25], v[146:149], v[210:213], v[22:25]
	v_mfma_f32_16x16x32_bf16 v[22:25], v[150:153], v[214:217], v[22:25]
	v_mfma_f32_16x16x32_bf16 v[18:21], v[176:179], v[210:213], v[18:21]
	v_mfma_f32_16x16x32_bf16 v[18:21], v[180:183], v[214:217], v[18:21]
	v_mfma_f32_16x16x32_bf16 v[6:9], v[146:149], v[218:221], v[6:9]
	v_mfma_f32_16x16x32_bf16 v[6:9], v[150:153], v[222:225], v[6:9]
	v_mfma_f32_16x16x32_bf16 v[2:5], v[176:179], v[218:221], v[2:5]
	v_mfma_f32_16x16x32_bf16 v[2:5], v[180:183], v[222:225], v[2:5]
	s_barrier
	s_add_i32 s66, s66, 2
	s_add_u32 s40, s40, 0x8000
	s_addc_u32 s41, s41, 0
	s_add_u32 s39, s39, 0x8000
	s_addc_u32 s65, s65, 0
	s_cmpk_gt_u32 s66, 0xfd
	s_cbranch_scc0 .LBB0_1292
	s_and_b64 vcc, exec, s[24:25]
	s_cbranch_vccz .LBB0_1295
	s_barrier

.LBB0_1387:
	ds_read_b128 v[62:65], v189
	ds_read_b128 v[66:69], v189 offset:1024
	ds_read_b128 v[74:77], v189 offset:2048
	ds_read_b128 v[78:81], v189 offset:3072
	ds_read_b128 v[146:149], v195
	ds_read_b128 v[150:153], v195 offset:1024
	ds_read_b128 v[154:157], v195 offset:2048
	ds_read_b128 v[158:161], v195 offset:3072
	s_add_u32 s34, s30, 0xfff04000
	s_addc_u32 s35, s31, -1
	s_cmp_eq_u32 s54, 60
	s_cselect_b32 s38, s27, s34
	s_cselect_b32 s39, s21, s35
	s_cselect_b32 s36, s29, s52
	s_cselect_b32 s37, s19, s53
	s_add_u32 s34, s38, 0x4000
	s_addc_u32 s35, s39, 0
	s_add_i32 m0, s40, 0xc000
	ds_read_b128 v[190:193], v197
	ds_read_b128 v[198:201], v197 offset:1024
	ds_read_b128 v[202:205], v197 offset:2048
	ds_read_b128 v[206:209], v197 offset:3072
	ds_read_b128 v[210:213], v197 offset:4096
	ds_read_b128 v[214:217], v197 offset:5120
	ds_read_b128 v[218:221], v197 offset:6144
	ds_read_b128 v[222:225], v197 offset:7168
	global_load_lds_dwordx4 v172, s[30:31]
	s_add_i32 m0, s40, 0xe000
	s_nop 0
	global_load_lds_dwordx4 v174, s[30:31]
	s_waitcnt vmcnt(8)
	s_waitcnt lgkmcnt(0)
	s_barrier
	s_waitcnt lgkmcnt(0)
	v_mfma_f32_16x16x32_bf16 v[142:145], v[62:65], v[190:193], v[142:145]
	v_mfma_f32_16x16x32_bf16 v[142:145], v[66:69], v[198:201], v[142:145]
	v_mfma_f32_16x16x32_bf16 v[138:141], v[74:77], v[190:193], v[138:141]
	v_mfma_f32_16x16x32_bf16 v[138:141], v[78:81], v[198:201], v[138:141]
	v_mfma_f32_16x16x32_bf16 v[126:129], v[62:65], v[202:205], v[126:129]
	v_mfma_f32_16x16x32_bf16 v[126:129], v[66:69], v[206:209], v[126:129]
	v_mfma_f32_16x16x32_bf16 v[122:125], v[74:77], v[202:205], v[122:125]
	v_mfma_f32_16x16x32_bf16 v[122:125], v[78:81], v[206:209], v[122:125]
	v_mfma_f32_16x16x32_bf16 v[110:113], v[62:65], v[210:213], v[110:113]
	v_mfma_f32_16x16x32_bf16 v[110:113], v[66:69], v[214:217], v[110:113]
	v_mfma_f32_16x16x32_bf16 v[106:109], v[74:77], v[210:213], v[106:109]
	v_mfma_f32_16x16x32_bf16 v[106:109], v[78:81], v[214:217], v[106:109]
	v_mfma_f32_16x16x32_bf16 v[94:97], v[62:65], v[218:221], v[94:97]
	v_mfma_f32_16x16x32_bf16 v[94:97], v[66:69], v[222:225], v[94:97]
	v_mfma_f32_16x16x32_bf16 v[90:93], v[74:77], v[218:221], v[90:93]
	v_mfma_f32_16x16x32_bf16 v[90:93], v[78:81], v[222:225], v[90:93]
	v_mfma_f32_16x16x32_bf16 v[134:137], v[146:149], v[190:193], v[134:137]
	v_mfma_f32_16x16x32_bf16 v[134:137], v[150:153], v[198:201], v[134:137]
	v_mfma_f32_16x16x32_bf16 v[130:133], v[154:157], v[190:193], v[130:133]
	v_mfma_f32_16x16x32_bf16 v[130:133], v[158:161], v[198:201], v[130:133]
	v_mfma_f32_16x16x32_bf16 v[118:121], v[146:149], v[202:205], v[118:121]
	v_mfma_f32_16x16x32_bf16 v[118:121], v[150:153], v[206:209], v[118:121]
	v_mfma_f32_16x16x32_bf16 v[114:117], v[154:157], v[202:205], v[114:117]
	v_mfma_f32_16x16x32_bf16 v[114:117], v[158:161], v[206:209], v[114:117]
	v_mfma_f32_16x16x32_bf16 v[102:105], v[146:149], v[210:213], v[102:105]
	v_mfma_f32_16x16x32_bf16 v[102:105], v[150:153], v[214:217], v[102:105]
	v_mfma_f32_16x16x32_bf16 v[98:101], v[154:157], v[210:213], v[98:101]
	v_mfma_f32_16x16x32_bf16 v[98:101], v[158:161], v[214:217], v[98:101]
	v_mfma_f32_16x16x32_bf16 v[86:89], v[146:149], v[218:221], v[86:89]
	v_mfma_f32_16x16x32_bf16 v[86:89], v[150:153], v[222:225], v[86:89]
	v_mfma_f32_16x16x32_bf16 v[82:85], v[154:157], v[218:221], v[82:85]
	v_mfma_f32_16x16x32_bf16 v[82:85], v[158:161], v[222:225], v[82:85]
	s_barrier
	s_add_i32 s55, s50, s33
	s_mov_b32 m0, s55
	ds_read_b128 v[190:193], v197 offset:16384
	ds_read_b128 v[198:201], v197 offset:17408
	ds_read_b128 v[202:205], v197 offset:18432
	ds_read_b128 v[206:209], v197 offset:19456
	ds_read_b128 v[210:213], v197 offset:20480
	ds_read_b128 v[214:217], v197 offset:21504
	ds_read_b128 v[218:221], v197 offset:22528
	ds_read_b128 v[222:225], v197 offset:23552
	global_load_lds_dwordx4 v166, s[36:37]
	s_add_i32 m0, s55, 0x2000
	s_add_u32 s56, s36, 0x100000
	s_addc_u32 s57, s37, 0
	s_add_i32 s55, s51, s33
	global_load_lds_dwordx4 v162, s[36:37]
	s_mov_b32 m0, s55
	s_nop 0
	global_load_lds_dwordx4 v166, s[56:57]
	s_add_i32 m0, s55, 0x2000
	s_nop 0
	global_load_lds_dwordx4 v162, s[56:57]
	s_mov_b32 m0, s40
	s_nop 0
	global_load_lds_dwordx4 v168, s[38:39]
	s_mov_b32 m0, s41
	s_nop 0
	global_load_lds_dwordx4 v164, s[38:39]
	s_waitcnt vmcnt(8)
	s_waitcnt lgkmcnt(0)
	s_barrier
	s_waitcnt lgkmcnt(0)
	v_mfma_f32_16x16x32_bf16 v[70:73], v[62:65], v[190:193], v[70:73]
	v_mfma_f32_16x16x32_bf16 v[70:73], v[66:69], v[198:201], v[70:73]
	v_mfma_f32_16x16x32_bf16 v[58:61], v[74:77], v[190:193], v[58:61]
	v_mfma_f32_16x16x32_bf16 v[58:61], v[78:81], v[198:201], v[58:61]
	v_mfma_f32_16x16x32_bf16 v[46:49], v[62:65], v[202:205], v[46:49]
	v_mfma_f32_16x16x32_bf16 v[46:49], v[66:69], v[206:209], v[46:49]
	v_mfma_f32_16x16x32_bf16 v[42:45], v[74:77], v[202:205], v[42:45]
	v_mfma_f32_16x16x32_bf16 v[42:45], v[78:81], v[206:209], v[42:45]
	v_mfma_f32_16x16x32_bf16 v[30:33], v[62:65], v[210:213], v[30:33]
	v_mfma_f32_16x16x32_bf16 v[30:33], v[66:69], v[214:217], v[30:33]
	v_mfma_f32_16x16x32_bf16 v[26:29], v[74:77], v[210:213], v[26:29]
	v_mfma_f32_16x16x32_bf16 v[26:29], v[78:81], v[214:217], v[26:29]
	v_mfma_f32_16x16x32_bf16 v[14:17], v[62:65], v[218:221], v[14:17]
	v_mfma_f32_16x16x32_bf16 v[14:17], v[66:69], v[222:225], v[14:17]
	v_mfma_f32_16x16x32_bf16 v[10:13], v[74:77], v[218:221], v[10:13]
	v_mfma_f32_16x16x32_bf16 v[10:13], v[78:81], v[222:225], v[10:13]
	v_mfma_f32_16x16x32_bf16 v[54:57], v[146:149], v[190:193], v[54:57]
	v_mfma_f32_16x16x32_bf16 v[54:57], v[150:153], v[198:201], v[54:57]
	v_mfma_f32_16x16x32_bf16 v[50:53], v[154:157], v[190:193], v[50:53]
	v_mfma_f32_16x16x32_bf16 v[50:53], v[158:161], v[198:201], v[50:53]
	v_mfma_f32_16x16x32_bf16 v[38:41], v[146:149], v[202:205], v[38:41]
	v_mfma_f32_16x16x32_bf16 v[38:41], v[150:153], v[206:209], v[38:41]
	v_mfma_f32_16x16x32_bf16 v[34:37], v[154:157], v[202:205], v[34:37]
	v_mfma_f32_16x16x32_bf16 v[34:37], v[158:161], v[206:209], v[34:37]
	v_mfma_f32_16x16x32_bf16 v[22:25], v[146:149], v[210:213], v[22:25]
	v_mfma_f32_16x16x32_bf16 v[22:25], v[150:153], v[214:217], v[22:25]
	v_mfma_f32_16x16x32_bf16 v[18:21], v[154:157], v[210:213], v[18:21]
	v_mfma_f32_16x16x32_bf16 v[18:21], v[158:161], v[214:217], v[18:21]
	v_mfma_f32_16x16x32_bf16 v[6:9], v[146:149], v[218:221], v[6:9]
	v_mfma_f32_16x16x32_bf16 v[6:9], v[150:153], v[222:225], v[6:9]
	v_mfma_f32_16x16x32_bf16 v[2:5], v[154:157], v[218:221], v[2:5]
	v_mfma_f32_16x16x32_bf16 v[2:5], v[158:161], v[222:225], v[2:5]
	s_barrier
	s_add_i32 s55, 0, 0x18000
	s_add_i32 s56, 0, 0x1c000
	v_add_u32_e32 v78, s55, v187
	v_add_u32_e32 v158, s56, v187
	ds_read_b128 v[62:65], v78
	ds_read_b128 v[66:69], v78 offset:1024
	ds_read_b128 v[74:77], v78 offset:2048
	ds_read_b128 v[78:81], v78 offset:3072
	ds_read_b128 v[146:149], v158
	ds_read_b128 v[150:153], v158 offset:1024
	ds_read_b128 v[154:157], v158 offset:2048
	ds_read_b128 v[158:161], v158 offset:3072
	s_add_u32 s38, s38, 0x100000
	s_addc_u32 s39, s39, 0
	s_mov_b32 m0, s42
	ds_read_b128 v[190:193], v197 offset:32768
	ds_read_b128 v[198:201], v197 offset:33792
	ds_read_b128 v[202:205], v197 offset:34816
	ds_read_b128 v[206:209], v197 offset:35840
	ds_read_b128 v[210:213], v197 offset:36864
	ds_read_b128 v[214:217], v197 offset:37888
	ds_read_b128 v[218:221], v197 offset:38912
	ds_read_b128 v[222:225], v197 offset:39936
	global_load_lds_dwordx4 v168, s[38:39]
	s_mov_b32 m0, s43
	s_nop 0
	global_load_lds_dwordx4 v164, s[38:39]
	s_waitcnt vmcnt(8)
	s_waitcnt lgkmcnt(0)
	s_barrier
	s_waitcnt lgkmcnt(0)
	v_mfma_f32_16x16x32_bf16 v[142:145], v[62:65], v[190:193], v[142:145]
	v_mfma_f32_16x16x32_bf16 v[142:145], v[66:69], v[198:201], v[142:145]
	v_mfma_f32_16x16x32_bf16 v[138:141], v[74:77], v[190:193], v[138:141]
	v_mfma_f32_16x16x32_bf16 v[138:141], v[78:81], v[198:201], v[138:141]
	v_mfma_f32_16x16x32_bf16 v[126:129], v[62:65], v[202:205], v[126:129]
	v_mfma_f32_16x16x32_bf16 v[126:129], v[66:69], v[206:209], v[126:129]
	v_mfma_f32_16x16x32_bf16 v[122:125], v[74:77], v[202:205], v[122:125]
	v_mfma_f32_16x16x32_bf16 v[122:125], v[78:81], v[206:209], v[122:125]
	v_mfma_f32_16x16x32_bf16 v[110:113], v[62:65], v[210:213], v[110:113]
	v_mfma_f32_16x16x32_bf16 v[110:113], v[66:69], v[214:217], v[110:113]
	v_mfma_f32_16x16x32_bf16 v[106:109], v[74:77], v[210:213], v[106:109]
	v_mfma_f32_16x16x32_bf16 v[106:109], v[78:81], v[214:217], v[106:109]
	v_mfma_f32_16x16x32_bf16 v[94:97], v[62:65], v[218:221], v[94:97]
	v_mfma_f32_16x16x32_bf16 v[94:97], v[66:69], v[222:225], v[94:97]
	v_mfma_f32_16x16x32_bf16 v[90:93], v[74:77], v[218:221], v[90:93]
	v_mfma_f32_16x16x32_bf16 v[90:93], v[78:81], v[222:225], v[90:93]
	v_mfma_f32_16x16x32_bf16 v[134:137], v[146:149], v[190:193], v[134:137]
	v_mfma_f32_16x16x32_bf16 v[134:137], v[150:153], v[198:201], v[134:137]
	v_mfma_f32_16x16x32_bf16 v[130:133], v[154:157], v[190:193], v[130:133]
	v_mfma_f32_16x16x32_bf16 v[130:133], v[158:161], v[198:201], v[130:133]
	v_mfma_f32_16x16x32_bf16 v[118:121], v[146:149], v[202:205], v[118:121]
	v_mfma_f32_16x16x32_bf16 v[118:121], v[150:153], v[206:209], v[118:121]
	v_mfma_f32_16x16x32_bf16 v[114:117], v[154:157], v[202:205], v[114:117]
	v_mfma_f32_16x16x32_bf16 v[114:117], v[158:161], v[206:209], v[114:117]
	v_mfma_f32_16x16x32_bf16 v[102:105], v[146:149], v[210:213], v[102:105]
	v_mfma_f32_16x16x32_bf16 v[102:105], v[150:153], v[214:217], v[102:105]
	v_mfma_f32_16x16x32_bf16 v[98:101], v[154:157], v[210:213], v[98:101]
	v_mfma_f32_16x16x32_bf16 v[98:101], v[158:161], v[214:217], v[98:101]
	v_mfma_f32_16x16x32_bf16 v[86:89], v[146:149], v[218:221], v[86:89]
	v_mfma_f32_16x16x32_bf16 v[86:89], v[150:153], v[222:225], v[86:89]
	v_mfma_f32_16x16x32_bf16 v[82:85], v[154:157], v[218:221], v[82:85]
	v_mfma_f32_16x16x32_bf16 v[82:85], v[158:161], v[222:225], v[82:85]
	s_barrier
	s_add_u32 s38, s36, 0x4000
	s_addc_u32 s39, s37, 0
	s_add_i32 s55, s55, s33
	s_mov_b32 m0, s55
	ds_read_b128 v[190:193], v197 offset:49152
	ds_read_b128 v[198:201], v197 offset:50176
	ds_read_b128 v[202:205], v197 offset:51200
	ds_read_b128 v[206:209], v197 offset:52224
	ds_read_b128 v[210:213], v197 offset:53248
	ds_read_b128 v[214:217], v197 offset:54272
	ds_read_b128 v[218:221], v197 offset:55296
	ds_read_b128 v[222:225], v197 offset:56320
	global_load_lds_dwordx4 v166, s[38:39]
	s_add_i32 m0, s55, 0x2000
	s_add_u32 s36, s36, 0x104000
	s_addc_u32 s37, s37, 0
	global_load_lds_dwordx4 v162, s[38:39]
	s_add_i32 s38, s56, s33
	s_mov_b32 m0, s38
	s_nop 0
	global_load_lds_dwordx4 v166, s[36:37]
	s_add_i32 m0, s38, 0x2000
	s_nop 0
	global_load_lds_dwordx4 v162, s[36:37]
	s_mov_b32 m0, s46
	s_nop 0
	global_load_lds_dwordx4 v168, s[34:35]
	s_mov_b32 m0, s47
	s_nop 0
	global_load_lds_dwordx4 v164, s[34:35]
	s_waitcnt vmcnt(8)
	s_waitcnt lgkmcnt(0)
	s_barrier
	s_waitcnt lgkmcnt(0)
	v_mfma_f32_16x16x32_bf16 v[70:73], v[62:65], v[190:193], v[70:73]
	v_mfma_f32_16x16x32_bf16 v[70:73], v[66:69], v[198:201], v[70:73]
	v_mfma_f32_16x16x32_bf16 v[58:61], v[74:77], v[190:193], v[58:61]
	v_mfma_f32_16x16x32_bf16 v[58:61], v[78:81], v[198:201], v[58:61]
	v_mfma_f32_16x16x32_bf16 v[46:49], v[62:65], v[202:205], v[46:49]
	v_mfma_f32_16x16x32_bf16 v[46:49], v[66:69], v[206:209], v[46:49]
	v_mfma_f32_16x16x32_bf16 v[42:45], v[74:77], v[202:205], v[42:45]
	v_mfma_f32_16x16x32_bf16 v[42:45], v[78:81], v[206:209], v[42:45]
	v_mfma_f32_16x16x32_bf16 v[30:33], v[62:65], v[210:213], v[30:33]
	v_mfma_f32_16x16x32_bf16 v[30:33], v[66:69], v[214:217], v[30:33]
	v_mfma_f32_16x16x32_bf16 v[26:29], v[74:77], v[210:213], v[26:29]
	v_mfma_f32_16x16x32_bf16 v[26:29], v[78:81], v[214:217], v[26:29]
	v_mfma_f32_16x16x32_bf16 v[14:17], v[62:65], v[218:221], v[14:17]
	v_mfma_f32_16x16x32_bf16 v[14:17], v[66:69], v[222:225], v[14:17]
	v_mfma_f32_16x16x32_bf16 v[10:13], v[74:77], v[218:221], v[10:13]
	v_mfma_f32_16x16x32_bf16 v[10:13], v[78:81], v[222:225], v[10:13]
	v_mfma_f32_16x16x32_bf16 v[54:57], v[146:149], v[190:193], v[54:57]
	v_mfma_f32_16x16x32_bf16 v[54:57], v[150:153], v[198:201], v[54:57]
	v_mfma_f32_16x16x32_bf16 v[50:53], v[154:157], v[190:193], v[50:53]
	v_mfma_f32_16x16x32_bf16 v[50:53], v[158:161], v[198:201], v[50:53]
	v_mfma_f32_16x16x32_bf16 v[38:41], v[146:149], v[202:205], v[38:41]
	v_mfma_f32_16x16x32_bf16 v[38:41], v[150:153], v[206:209], v[38:41]
	v_mfma_f32_16x16x32_bf16 v[34:37], v[154:157], v[202:205], v[34:37]
	v_mfma_f32_16x16x32_bf16 v[34:37], v[158:161], v[206:209], v[34:37]
	v_mfma_f32_16x16x32_bf16 v[22:25], v[146:149], v[210:213], v[22:25]
	v_mfma_f32_16x16x32_bf16 v[22:25], v[150:153], v[214:217], v[22:25]
	v_mfma_f32_16x16x32_bf16 v[18:21], v[154:157], v[210:213], v[18:21]
	v_mfma_f32_16x16x32_bf16 v[18:21], v[158:161], v[214:217], v[18:21]
	v_mfma_f32_16x16x32_bf16 v[6:9], v[146:149], v[218:221], v[6:9]
	v_mfma_f32_16x16x32_bf16 v[6:9], v[150:153], v[222:225], v[6:9]
	v_mfma_f32_16x16x32_bf16 v[2:5], v[154:157], v[218:221], v[2:5]
	v_mfma_f32_16x16x32_bf16 v[2:5], v[158:161], v[222:225], v[2:5]
	s_barrier
	s_add_i32 s54, s54, 2
	s_add_u32 s30, s30, 0x8000
	s_addc_u32 s31, s31, 0
	s_add_u32 s52, s52, 0x8000
	s_addc_u32 s53, s53, 0
	s_cmp_gt_u32 s54, 61
	s_cbranch_scc0 .LBB0_1387
	s_and_b64 vcc, exec, s[12:13]
	s_cbranch_vccz .LBB0_1390
	s_barrier
